# P9 conv epilogue: weights/bias prefetched one unit ahead into spare LDS by LDS-DMA, read with ds_read_b128; no vmcnt wait before main loop
# speedup vs baseline: 1.0098x; 1.0028x over previous
; #define PG8_STAGE(bufoff, gbase, voff) do { _Pragma("unroll") for (int _i = 0; _i < 2; ++_i) \
;         __builtin_amdgcn_global_load_lds((const unsigned*)((const char*)(gbase) + (voff)[_i]), (PG8_LAS unsigned*)(lds + (bufoff) + ldsw + _i * 8192), 16, 0, 0); } while (0)
; #define PG8_WAIT_V(n) asm volatile("s_waitcnt vmcnt(" #n ")" ::: "memory")
; #define PG8_BAR __builtin_amdgcn_s_barrier()
; template <class Epi, class Sched, bool ALIGN_EPI = false, bool SP2 = false>
; __device__ __forceinline__ void gemm_phase(PG8_LAS unsigned char* lds, const Gemm g, const Sched& S, const Epi& E, int wv) {
;     ...
;         PG8_STAGE(PG8_SB(0, 0), cB, voffB); PG8_STAGE(PG8_SB(0, 1), cB + hstepB, voffB); PG8_STAGE(PG8_SA(0, 0), cA, voffA); PG8_STAGE(PG8_SA(0, 1), cA + hstepA, voffA);
;         if (wr == 1) PG8_BAR;
;         PG8_WAIT_V(2); PG8_BAR;
;         PG8_STAGE(PG8_SB(1, 0), cB + kstep, voffB); PG8_STAGE(PG8_SA(1, 0), cA + kstep, voffA); PG8_STAGE(PG8_SB(1, 1), cB + hstepB + kstep, voffB);
;         PG8_WAIT_V(6); PG8_BAR;
; __device__ __forceinline__ void phase10(const Args& a, int G, int wv, bool dummy = false) {
;     ...
;     for (int it = gw; it < 256 * 22; it += NGW) {
;         const int rs = it / 22, cs = it % 22, row0 = rs * 64, pn = 2 * cs + (lane >> 5), j = (lane & 31) * 4, col = 256 * pn + j, ch = 128 * pn + j; constexpr size_t VPL = (size_t)16384 * 5632;
;         const f32x4 wg0 = *(const f32x4*)(cw + ch), wg1 = *(const f32x4*)(cw + 11264 + ch), wg2 = *(const f32x4*)(cw + 22528 + ch), bg = *(const f32x4*)(cb + ch);
;         const f32x4 wv0 = *(const f32x4*)(cw + 5632 + ch), wv1 = *(const f32x4*)(cw + 11264 + 5632 + ch), wv2 = *(const f32x4*)(cw + 22528 + 5632 + ch), bv = *(const f32x4*)(cb + 5632 + ch);
.LBB0_959:
	s_add_u32 s12, s78, 0x9300000
	s_addc_u32 s13, s79, 0
	s_add_u32 s14, s78, 0x1f300000
	s_addc_u32 s15, s79, 0
	s_add_u32 s4, s34, 0x80080
	s_mov_b64 s[16:17], 0x80
	s_addc_u32 s5, s35, 0
	s_add_i32 m0, s45, 0x18000
	v_lshl_add_u64 v[6:7], v[6:7], 0, s[16:17]
	s_waitcnt vmcnt(2)
	s_barrier
	global_load_lds_dwordx4 v[6:7], off
	v_lshl_add_u64 v[4:5], v[4:5], 0, s[16:17]
	s_add_i32 m0, s45, 0x1a000
	s_add_i32 s49, s45, 0x8000
	global_load_lds_dwordx4 v[4:5], off
	v_lshl_add_u64 v[0:1], v[0:1], 0, s[16:17]
	s_mov_b32 m0, s49
	s_add_i32 s50, s45, 0xa000
	global_load_lds_dwordx4 v[0:1], off
	v_lshl_add_u64 v[0:1], v[2:3], 0, s[16:17]
	s_mov_b32 m0, s50
	v_and_b32_e32 v150, 15, v8
	global_load_lds_dwordx4 v[0:1], off
	s_add_i32 m0, s45, 0x1c000
	v_lshl_add_u64 v[0:1], s[4:5], 0, v[132:133]
	global_load_lds_dwordx4 v[0:1], off
	v_lshl_add_u64 v[0:1], s[4:5], 0, v[128:129]
	s_add_i32 m0, s45, 0x1e000
	v_lshlrev_b32_e32 v2, 2, v8
	global_load_lds_dwordx4 v[0:1], off
	v_lshrrev_b32_e32 v0, 1, v8
	v_and_b32_e32 v0, 24, v0
	v_lshlrev_b32_e32 v1, 1, v0
	s_sext_i32_i16 s29, s2
	v_lshl_or_b32 v1, v150, 6, v1
	s_lshl_b32 s2, s18, 13
	v_and_b32_e32 v2, 32, v2
	v_bitop3_b32 v3, v1, s2, v2 bitop3:0xde
	s_lshl_b32 s2, s8, 5
	s_and_b32 s4, s2, 0x60
	s_lshl_b32 s2, s4, 7
	v_bitop3_b32 v151, v1, s2, v2 bitop3:0xde
	v_lshlrev_b32_e32 v1, 15, v13
	v_and_b32_e32 v1, 0xffff0000, v1
	v_lshl_add_u32 v1, v12, 12, v1
	v_and_b32_e32 v2, 1, v13
	v_lshl_or_b32 v1, v2, 6, v1
	v_lshl_add_u32 v140, v14, 1, v1
	v_lshlrev_b32_e32 v1, 15, v9
	s_ashr_i32 s51, s89, 31
	s_lshl_b32 s52, s18, 6
	v_and_b32_e32 v1, 0xffff0000, v1
	s_waitcnt vmcnt(6)
	s_cmpk_lt_u32 s3, 0x100
	v_lshl_add_u32 v1, v10, 12, v1
	v_and_b32_e32 v2, 1, v9
	s_cselect_b64 s[18:19], -1, 0
	v_lshl_or_b32 v1, v2, 6, v1
	s_add_i32 s53, 0, 0x10000
	s_add_i32 s54, 0, 0x14000
	v_cmp_lt_u32_e64 s[2:3], 13, v150
	v_add_u32_e32 v138, -14, v150
	v_mov_b32_e32 v139, v137
	v_or_b32_e32 v152, s4, v0
	v_mov_b32_e32 v141, v137
	v_lshl_add_u32 v142, v11, 1, v1
	v_mov_b32_e32 v143, v137
	v_mov_b64_e32 v[144:145], 0xb00
	v_mov_b64_e32 v[146:147], 0xaff
	v_add_u32_e32 v153, s53, v151
	v_add_u32_e32 v154, s54, v151
	v_add_u32_e32 v155, 0, v3
	s_movk_i32 s55, 0x5800
	s_movk_i32 s56, 0x2c00
	s_lshl_b32 s8, s4, 1
	v_lshlrev_b32_e32 v136, 1, v0
	s_mov_b32 s57, 0xb000000
	s_mov_b32 s58, s9
	s_barrier
	s_load_dwordx4 s[72:75], s[0:1], 0xa8
	s_lshr_b32 s68, s90, 6
	s_and_b32 s69, s68, 3
	s_lshr_b32 s70, s68, 2
	s_mul_i32 s71, s70, 0x5800
	s_mul_i32 s94, s69, 0xb000
	s_lshl_b32 s67, s68, 9
	s_add_i32 s67, s67, 0x20000
	s_mov_b32 s95, 0
	v_mbcnt_lo_u32_b32 v228, -1, 0
	v_mbcnt_hi_u32_b32 v228, -1, v228
	v_lshlrev_b32_e32 v228, 4, v228
	s_waitcnt lgkmcnt(0)
	s_cmp_eq_u32 s69, 3
	s_cselect_b32 s92, s74, s72
	s_cselect_b32 s93, s75, s73
	s_cselect_b32 s94, 0, s94
	s_add_i32 s94, s94, s71
	s_add_u32 s76, s92, s94
	s_addc_u32 s77, s93, 0
	s_lshl_b32 s94, s29, 9
	s_add_u32 s92, s76, s94
	s_addc_u32 s93, s77, 0
	s_mov_b32 m0, s67
	s_mov_b32 exec_lo, -1
	s_mov_b32 exec_hi, 0
	s_nop 0
	global_load_lds_dwordx4 v228, s[92:93]
	s_mov_b64 exec, -1
	s_branch .LBB0_962

;     __device__ __forceinline__ void operator()(const f32x4 (&acc)[2][2][4][2], const Unit& u, int wr, int wc, int fr, int fq) const {
;     ...
;             for (int m = 0; m < 4; ++m) { const int row = row0 + ai * HALF + m * 16; bf16_t* rowp = UP + (size_t)row * 5632 + u.pn * HALF + wc * 32 + 8 * fq;
; #pragma unroll
;                 for (int bj = 0; bj < 2; ++bj) { const u32x4 w = pack8(acc[ai][bj][m][0], acc[ai][bj][m][1]); __builtin_nontemporal_store(w, (u32x4*)(rowp + (size_t)bj * ((size_t)16384 * 5632)));
; __device__ __forceinline__ void phase10(const Args& a, int G, int wv, bool dummy = false) {
;     ...
;         const f32x4 wg0 = *(const f32x4*)(cw + ch), wg1 = *(const f32x4*)(cw + 11264 + ch), wg2 = *(const f32x4*)(cw + 22528 + ch), bg = *(const f32x4*)(cb + ch);
;         const f32x4 wv0 = *(const f32x4*)(cw + 5632 + ch), wv1 = *(const f32x4*)(cw + 11264 + 5632 + ch), wv2 = *(const f32x4*)(cw + 22528 + 5632 + ch), bv = *(const f32x4*)(cb + 5632 + ch);
;         f32x4 gm2 = {0.f, 0.f, 0.f, 0.f}, gm1 = gm2, vm2 = gm2, vm1 = gm2;
;         if (row0 & 2047) { const bf16_t* hp = HALO + (size_t)(rs - 1) * 2 * 11264 + col;
;             gm2 = bf4(*(const u32x2*)hp); gm1 = bf4(*(const u32x2*)(hp + 11264)); vm2 = bf4(*(const u32x2*)(hp + 128)); vm1 = bf4(*(const u32x2*)(hp + 11264 + 128)); }
;         bf16_t* up = UP + (size_t)row0 * 5632 + ch;
;         for (int t0 = 0; t0 < 64; t0 += 8) {
;             u32x2 gr[8], vr[8];
; #pragma unroll
;             for (int t = 0; t < 8; ++t) { gr[t] = __builtin_nontemporal_load((const u32x2*)(up + (size_t)(t0 + t) * 5632)); vr[t] = __builtin_nontemporal_load((const u32x2*)(up + VPL + (size_t)(t0 + t) * 5632)); }
; #pragma unroll
;             for (int t = 0; t < 8; ++t) { const f32x4 gc = bf4(gr[t]), vc = bf4(vr[t]);
;                 const f32x4 gg = wg0 * gm2 + wg1 * gm1 + wg2 * gc + bg, vv = wv0 * vm2 + wv1 * vm1 + wv2 * vc + bv;
;                 f32x4 o;
; #pragma unroll
;                 for (int e = 0; e < 4; ++e) o[e] = gg[e] * pg8::sigmoid_f(gg[e]) * vv[e];
;                 u32x2 w; w.x = cvt_pk_bf16(o[0], o[1]); w.y = cvt_pk_bf16(o[2], o[3]);
;                 if (dummy) *(u32x2*)((bf16_t*)(a.ws + WS_D) + ((((size_t)(row0 + t0 + t)) * 5632 + ch) & (size_t)0x1ffffff)) = w; else *(u32x2*)(up + (size_t)(t0 + t) * 5632) = w;
;                 gm2 = gm1; gm1 = gc; vm2 = vm1; vm1 = vc; }
.LBB0_968:
	s_mov_b32 s98, s28
	s_mov_b32 s99, s29
	s_and_b64 vcc, exec, s[4:5]
	s_cbranch_vccz .Lcw_nonext
	v_mbcnt_lo_u32_b32 v228, -1, 0
	v_mbcnt_hi_u32_b32 v228, -1, v228
	v_lshlrev_b32_e32 v228, 4, v228
	s_lshl_b32 s94, s20, 9
	s_add_u32 s92, s76, s94
	s_addc_u32 s93, s77, 0
	s_xor_b32 s96, s95, 0x1000
	s_add_i32 m0, s67, s96
	s_mov_b32 exec_lo, -1
	s_mov_b32 exec_hi, 0
	s_nop 0
	global_load_lds_dwordx4 v228, s[92:93]
	s_mov_b64 exec, -1
.Lcw_nonext:
	v_lshlrev_b32_e32 v148, 2, v152
	v_add_u32_e32 v148, s95, v148
	v_add_u32_e32 v148, 0x20000, v148
	ds_read_b128 v[156:159], v148
	ds_read_b128 v[160:163], v148 offset:16
	ds_read_b128 v[164:167], v148 offset:512
	ds_read_b128 v[168:171], v148 offset:528
	ds_read_b128 v[172:175], v148 offset:1024
	ds_read_b128 v[176:179], v148 offset:1040
	ds_read_b128 v[180:183], v148 offset:1536
	ds_read_b128 v[184:187], v148 offset:1552
	ds_read_b128 v[188:191], v148 offset:2048
	ds_read_b128 v[192:195], v148 offset:2064
	ds_read_b128 v[196:199], v148 offset:2560
	ds_read_b128 v[200:203], v148 offset:2576
	ds_read_b128 v[204:207], v148 offset:3072
	ds_read_b128 v[208:211], v148 offset:3088
	ds_read_b128 v[212:215], v148 offset:3584
	ds_read_b128 v[216:219], v148 offset:3600
	s_xor_b32 s95, s95, 0x1000
	v_add_u32_e32 v149, s52, v150
	v_mul_u32_u24_e32 v149, 0x2c00, v149
	v_lshl_add_u32 v149, v152, 1, v149
	v_mul_u32_u24_e32 v221, 0x5800, v150
	v_lshl_add_u32 v221, v152, 1, v221
	v_add_u32_e32 v220, 0xfffb3000, v221
	v_cmp_gt_u32_e64 s[64:65], 2, v150
	v_mov_b32_e32 v236, 0xbfb8aa3b
	v_mov_b32_e32 v238, 1.0
	v_mov_b32_e32 v239, 1.0
	s_lshl_b32 s21, s99, 9
	s_lshl_b32 s63, s98, 2
	s_lshr_b32 s66, s52, 6
	s_add_i32 s63, s63, s66
	s_mul_i32 s63, s63, 0xb000
	s_add_i32 s63, s63, s21
	s_add_u32 s34, s14, s63
	s_addc_u32 s35, s15, 0
	s_add_u32 s36, s12, 0xb000000
	s_addc_u32 s37, s13, 0
	s_add_u32 s36, s36, s63
	s_addc_u32 s37, s37, 0
	v_cvt_pk_bf16_f32 v222, v80, v81
	v_cvt_pk_bf16_f32 v223, v82, v83
	v_cvt_pk_bf16_f32 v224, v72, v73
	v_cvt_pk_bf16_f32 v225, v74, v75
	s_mov_b64 exec, s[2:3]
	global_store_dwordx4 v220, v[222:225], s[34:35]
	s_mov_b64 exec, -1
	v_cvt_pk_bf16_f32 v226, v68, v69
	v_cvt_pk_bf16_f32 v227, v70, v71
	v_cvt_pk_bf16_f32 v228, v64, v65
	v_cvt_pk_bf16_f32 v229, v66, v67
	s_mov_b64 exec, s[2:3]
	global_store_dwordx4 v220, v[226:229], s[34:35] offset:256
	s_mov_b64 exec, -1
	v_cvt_pk_bf16_f32 v230, v124, v125
	v_cvt_pk_bf16_f32 v231, v126, v127
	v_cvt_pk_bf16_f32 v232, v120, v121
	v_cvt_pk_bf16_f32 v233, v122, v123
	s_mov_b64 exec, s[64:65]
	global_store_dwordx4 v221, v[230:233], s[36:37]
	s_mov_b64 exec, -1
	v_cvt_pk_bf16_f32 v240, v116, v117
	v_cvt_pk_bf16_f32 v241, v118, v119
	v_cvt_pk_bf16_f32 v242, v108, v109
	v_cvt_pk_bf16_f32 v243, v110, v111
	s_mov_b64 exec, s[64:65]
	global_store_dwordx4 v221, v[240:243], s[36:37] offset:256
	s_mov_b64 exec, -1
	s_add_u32 s34, s34, 0x16000
	s_addc_u32 s35, s35, 0
	s_add_u32 s36, s36, 0x16000
	s_addc_u32 s37, s37, 0
	v_cvt_pk_bf16_f32 v222, v16, v17
	v_cvt_pk_bf16_f32 v223, v18, v19
	v_cvt_pk_bf16_f32 v224, v8, v9
	v_cvt_pk_bf16_f32 v225, v10, v11
	s_mov_b64 exec, s[2:3]
	global_store_dwordx4 v220, v[222:225], s[34:35]
	s_mov_b64 exec, -1
	v_cvt_pk_bf16_f32 v226, v4, v5
	v_cvt_pk_bf16_f32 v227, v6, v7
	v_cvt_pk_bf16_f32 v228, v0, v1
	v_cvt_pk_bf16_f32 v229, v2, v3
	s_mov_b64 exec, s[2:3]
	global_store_dwordx4 v220, v[226:229], s[34:35] offset:256
	s_mov_b64 exec, -1
	v_cvt_pk_bf16_f32 v230, v60, v61
	v_cvt_pk_bf16_f32 v231, v62, v63
	v_cvt_pk_bf16_f32 v232, v56, v57
	v_cvt_pk_bf16_f32 v233, v58, v59
	s_mov_b64 exec, s[64:65]
	global_store_dwordx4 v221, v[230:233], s[36:37]
	s_mov_b64 exec, -1
	v_cvt_pk_bf16_f32 v240, v52, v53
	v_cvt_pk_bf16_f32 v241, v54, v55
	v_cvt_pk_bf16_f32 v242, v44, v45
	v_cvt_pk_bf16_f32 v243, v46, v47
	s_mov_b64 exec, s[64:65]
	global_store_dwordx4 v221, v[240:243], s[36:37] offset:256
	s_mov_b64 exec, -1
	s_waitcnt lgkmcnt(0)
	s_nop 4
	s_mul_i32 s63, s98, 0x2c0000
	s_lshl_b32 s66, s99, 8
	s_add_u32 s63, s63, s66
	s_add_u32 s100, s12, s63
	s_addc_u32 s101, s13, 0
	v_pk_fma_f32 v[232:233], v[80:81], v[172:173], v[180:181]
	v_pk_fma_f32 v[234:235], v[68:69], v[204:205], v[212:213]
	s_nop 1
	v_fmac_f32_dpp v232, v80, v164 row_shr:1 row_mask:0xf bank_mask:0xf
	v_fmac_f32_dpp v233, v81, v165 row_shr:1 row_mask:0xf bank_mask:0xf
	v_fmac_f32_dpp v234, v68, v196 row_shr:1 row_mask:0xf bank_mask:0xf
	v_fmac_f32_dpp v235, v69, v197 row_shr:1 row_mask:0xf bank_mask:0xf
	v_fmac_f32_dpp v232, v80, v156 row_shr:2 row_mask:0xf bank_mask:0xf
	v_fmac_f32_dpp v233, v81, v157 row_shr:2 row_mask:0xf bank_mask:0xf
	v_fmac_f32_dpp v234, v68, v188 row_shr:2 row_mask:0xf bank_mask:0xf
	v_fmac_f32_dpp v235, v69, v189 row_shr:2 row_mask:0xf bank_mask:0xf
	v_fmac_f32_dpp v232, v96, v164 row_shl:15 row_mask:0xf bank_mask:0xf
	v_fmac_f32_dpp v233, v97, v165 row_shl:15 row_mask:0xf bank_mask:0xf
	v_fmac_f32_dpp v234, v84, v196 row_shl:15 row_mask:0xf bank_mask:0xf
	v_fmac_f32_dpp v235, v85, v197 row_shl:15 row_mask:0xf bank_mask:0xf
	v_fmac_f32_dpp v232, v96, v156 row_shl:14 row_mask:0xf bank_mask:0xf
	v_fmac_f32_dpp v233, v97, v157 row_shl:14 row_mask:0xf bank_mask:0xf
	v_fmac_f32_dpp v234, v84, v188 row_shl:14 row_mask:0xf bank_mask:0xf
	v_fmac_f32_dpp v235, v85, v189 row_shl:14 row_mask:0xf bank_mask:0xf
	v_mul_f32_e32 v246, v236, v232
	v_mul_f32_e32 v247, v236, v233
	v_exp_f32_e32 v246, v246
	v_exp_f32_e32 v247, v247
	s_nop 0
	v_pk_add_f32 v[246:247], v[246:247], v[238:239]
	v_rcp_f32_e32 v246, v246
	v_rcp_f32_e32 v247, v247
	v_pk_mul_f32 v[232:233], v[232:233], v[234:235]
	v_pk_mul_f32 v[232:233], v[232:233], v[246:247]
	v_cvt_pk_bf16_f32 v80, v232, v233
; __device__ __forceinline__ unsigned cvt_pk_bf16(float lo, float hi) { unsigned r; asm("v_cvt_pk_bf16_f32 %0, %1, %2" : "=v"(r) : "v"(lo), "v"(hi)); return r; }
; __device__ __forceinline__ float sigmoid_f(float v) { return __builtin_amdgcn_rcpf(1.0f + __builtin_amdgcn_exp2f(-1.4426950409f * v)); }
; __device__ __forceinline__ f32x4 bf4(u32x2 w) { return (f32x4){bf_lo(w.x), bf_hi(w.x), bf_lo(w.y), bf_hi(w.y)}; }
; __device__ __forceinline__ void phase10(const Args& a, int G, int wv, bool dummy = false) {
;     ...
;             for (int t = 0; t < 8; ++t) { const f32x4 gc = bf4(gr[t]), vc = bf4(vr[t]);
;                 const f32x4 gg = wg0 * gm2 + wg1 * gm1 + wg2 * gc + bg, vv = wv0 * vm2 + wv1 * vm1 + wv2 * vc + bv;
;                 f32x4 o;
; #pragma unroll
;                 for (int e = 0; e < 4; ++e) o[e] = gg[e] * pg8::sigmoid_f(gg[e]) * vv[e];
;                 u32x2 w; w.x = cvt_pk_bf16(o[0], o[1]); w.y = cvt_pk_bf16(o[2], o[3]);
;                 if (dummy) *(u32x2*)((bf16_t*)(a.ws + WS_D) + ((((size_t)(row0 + t0 + t)) * 5632 + ch) & (size_t)0x1ffffff)) = w; else *(u32x2*)(up + (size_t)(t0 + t) * 5632) = w;
;                 gm2 = gm1; gm1 = gc; vm2 = vm1; vm1 = vc; }
	v_pk_fma_f32 v[232:233], v[96:97], v[172:173], v[180:181]
	v_pk_fma_f32 v[234:235], v[84:85], v[204:205], v[212:213]
	s_nop 1
	v_fmac_f32_dpp v232, v96, v164 row_shr:1 row_mask:0xf bank_mask:0xf
	v_fmac_f32_dpp v233, v97, v165 row_shr:1 row_mask:0xf bank_mask:0xf
	v_fmac_f32_dpp v234, v84, v196 row_shr:1 row_mask:0xf bank_mask:0xf
	v_fmac_f32_dpp v235, v85, v197 row_shr:1 row_mask:0xf bank_mask:0xf
	v_fmac_f32_dpp v232, v96, v156 row_shr:2 row_mask:0xf bank_mask:0xf
	v_fmac_f32_dpp v233, v97, v157 row_shr:2 row_mask:0xf bank_mask:0xf
	v_fmac_f32_dpp v234, v84, v188 row_shr:2 row_mask:0xf bank_mask:0xf
	v_fmac_f32_dpp v235, v85, v189 row_shr:2 row_mask:0xf bank_mask:0xf
	v_fmac_f32_dpp v232, v112, v164 row_shl:15 row_mask:0xf bank_mask:0xf
	v_fmac_f32_dpp v233, v113, v165 row_shl:15 row_mask:0xf bank_mask:0xf
	v_fmac_f32_dpp v234, v100, v196 row_shl:15 row_mask:0xf bank_mask:0xf
	v_fmac_f32_dpp v235, v101, v197 row_shl:15 row_mask:0xf bank_mask:0xf
	v_fmac_f32_dpp v232, v112, v156 row_shl:14 row_mask:0xf bank_mask:0xf
	v_fmac_f32_dpp v233, v113, v157 row_shl:14 row_mask:0xf bank_mask:0xf
	v_fmac_f32_dpp v234, v100, v188 row_shl:14 row_mask:0xf bank_mask:0xf
	v_fmac_f32_dpp v235, v101, v189 row_shl:14 row_mask:0xf bank_mask:0xf
	v_mul_f32_e32 v246, v236, v232
	v_mul_f32_e32 v247, v236, v233
	v_exp_f32_e32 v246, v246
	v_exp_f32_e32 v247, v247
	s_nop 0
	v_pk_add_f32 v[246:247], v[246:247], v[238:239]
	v_rcp_f32_e32 v246, v246
	v_rcp_f32_e32 v247, v247
	v_pk_mul_f32 v[232:233], v[232:233], v[234:235]
	v_pk_mul_f32 v[232:233], v[232:233], v[246:247]
	v_cvt_pk_bf16_f32 v96, v232, v233
	v_pk_fma_f32 v[232:233], v[112:113], v[172:173], v[180:181]
	v_pk_fma_f32 v[234:235], v[100:101], v[204:205], v[212:213]
	s_nop 1
	v_fmac_f32_dpp v232, v112, v164 row_shr:1 row_mask:0xf bank_mask:0xf
	v_fmac_f32_dpp v233, v113, v165 row_shr:1 row_mask:0xf bank_mask:0xf
	v_fmac_f32_dpp v234, v100, v196 row_shr:1 row_mask:0xf bank_mask:0xf
	v_fmac_f32_dpp v235, v101, v197 row_shr:1 row_mask:0xf bank_mask:0xf
	v_fmac_f32_dpp v232, v112, v156 row_shr:2 row_mask:0xf bank_mask:0xf
	v_fmac_f32_dpp v233, v113, v157 row_shr:2 row_mask:0xf bank_mask:0xf
	v_fmac_f32_dpp v234, v100, v188 row_shr:2 row_mask:0xf bank_mask:0xf
	v_fmac_f32_dpp v235, v101, v189 row_shr:2 row_mask:0xf bank_mask:0xf
	v_fmac_f32_dpp v232, v124, v164 row_shl:15 row_mask:0xf bank_mask:0xf
	v_fmac_f32_dpp v233, v125, v165 row_shl:15 row_mask:0xf bank_mask:0xf
	v_fmac_f32_dpp v234, v116, v196 row_shl:15 row_mask:0xf bank_mask:0xf
	v_fmac_f32_dpp v235, v117, v197 row_shl:15 row_mask:0xf bank_mask:0xf
	v_fmac_f32_dpp v232, v124, v156 row_shl:14 row_mask:0xf bank_mask:0xf
	v_fmac_f32_dpp v233, v125, v157 row_shl:14 row_mask:0xf bank_mask:0xf
	v_fmac_f32_dpp v234, v116, v188 row_shl:14 row_mask:0xf bank_mask:0xf
	v_fmac_f32_dpp v235, v117, v189 row_shl:14 row_mask:0xf bank_mask:0xf
	v_mul_f32_e32 v246, v236, v232
	v_mul_f32_e32 v247, v236, v233
	v_exp_f32_e32 v246, v246
	v_exp_f32_e32 v247, v247
	s_nop 0
	v_pk_add_f32 v[246:247], v[246:247], v[238:239]
	v_rcp_f32_e32 v246, v246
	v_rcp_f32_e32 v247, v247
	v_pk_mul_f32 v[232:233], v[232:233], v[234:235]
	v_pk_mul_f32 v[232:233], v[232:233], v[246:247]
	v_cvt_pk_bf16_f32 v112, v232, v233
	v_pk_fma_f32 v[232:233], v[124:125], v[172:173], v[180:181]
	v_pk_fma_f32 v[234:235], v[116:117], v[204:205], v[212:213]
	s_nop 1
	v_fmac_f32_dpp v232, v124, v164 row_shr:1 row_mask:0xf bank_mask:0xf
	v_fmac_f32_dpp v233, v125, v165 row_shr:1 row_mask:0xf bank_mask:0xf
	v_fmac_f32_dpp v234, v116, v196 row_shr:1 row_mask:0xf bank_mask:0xf
	v_fmac_f32_dpp v235, v117, v197 row_shr:1 row_mask:0xf bank_mask:0xf
	v_fmac_f32_dpp v232, v124, v156 row_shr:2 row_mask:0xf bank_mask:0xf
	v_fmac_f32_dpp v233, v125, v157 row_shr:2 row_mask:0xf bank_mask:0xf
	v_fmac_f32_dpp v234, v116, v188 row_shr:2 row_mask:0xf bank_mask:0xf
	v_fmac_f32_dpp v235, v117, v189 row_shr:2 row_mask:0xf bank_mask:0xf
	v_mul_f32_e32 v246, v236, v232
	v_mul_f32_e32 v247, v236, v233
	v_exp_f32_e32 v246, v246
	v_exp_f32_e32 v247, v247
	s_nop 0
	v_pk_add_f32 v[246:247], v[246:247], v[238:239]
	v_rcp_f32_e32 v246, v246
	v_rcp_f32_e32 v247, v247
	v_pk_mul_f32 v[232:233], v[232:233], v[234:235]
	v_pk_mul_f32 v[232:233], v[232:233], v[246:247]
	v_cvt_pk_bf16_f32 v124, v232, v233
	v_pk_fma_f32 v[232:233], v[82:83], v[174:175], v[182:183]
	v_pk_fma_f32 v[234:235], v[70:71], v[206:207], v[214:215]
	s_nop 1
	v_fmac_f32_dpp v232, v82, v166 row_shr:1 row_mask:0xf bank_mask:0xf
	v_fmac_f32_dpp v233, v83, v167 row_shr:1 row_mask:0xf bank_mask:0xf
	v_fmac_f32_dpp v234, v70, v198 row_shr:1 row_mask:0xf bank_mask:0xf
	v_fmac_f32_dpp v235, v71, v199 row_shr:1 row_mask:0xf bank_mask:0xf
	v_fmac_f32_dpp v232, v82, v158 row_shr:2 row_mask:0xf bank_mask:0xf
	v_fmac_f32_dpp v233, v83, v159 row_shr:2 row_mask:0xf bank_mask:0xf
	v_fmac_f32_dpp v234, v70, v190 row_shr:2 row_mask:0xf bank_mask:0xf
	v_fmac_f32_dpp v235, v71, v191 row_shr:2 row_mask:0xf bank_mask:0xf
	v_fmac_f32_dpp v232, v98, v166 row_shl:15 row_mask:0xf bank_mask:0xf
	v_fmac_f32_dpp v233, v99, v167 row_shl:15 row_mask:0xf bank_mask:0xf
	v_fmac_f32_dpp v234, v86, v198 row_shl:15 row_mask:0xf bank_mask:0xf
	v_fmac_f32_dpp v235, v87, v199 row_shl:15 row_mask:0xf bank_mask:0xf
	v_fmac_f32_dpp v232, v98, v158 row_shl:14 row_mask:0xf bank_mask:0xf
	v_fmac_f32_dpp v233, v99, v159 row_shl:14 row_mask:0xf bank_mask:0xf
	v_fmac_f32_dpp v234, v86, v190 row_shl:14 row_mask:0xf bank_mask:0xf
	v_fmac_f32_dpp v235, v87, v191 row_shl:14 row_mask:0xf bank_mask:0xf
	v_mul_f32_e32 v246, v236, v232
	v_mul_f32_e32 v247, v236, v233
	v_exp_f32_e32 v246, v246
	v_exp_f32_e32 v247, v247
	s_nop 0
; __device__ __forceinline__ unsigned cvt_pk_bf16(float lo, float hi) { unsigned r; asm("v_cvt_pk_bf16_f32 %0, %1, %2" : "=v"(r) : "v"(lo), "v"(hi)); return r; }
; __device__ __forceinline__ float sigmoid_f(float v) { return __builtin_amdgcn_rcpf(1.0f + __builtin_amdgcn_exp2f(-1.4426950409f * v)); }
; __device__ __forceinline__ f32x4 bf4(u32x2 w) { return (f32x4){bf_lo(w.x), bf_hi(w.x), bf_lo(w.y), bf_hi(w.y)}; }
; __device__ __forceinline__ void phase10(const Args& a, int G, int wv, bool dummy = false) {
;     ...
;             for (int t = 0; t < 8; ++t) { const f32x4 gc = bf4(gr[t]), vc = bf4(vr[t]);
;                 const f32x4 gg = wg0 * gm2 + wg1 * gm1 + wg2 * gc + bg, vv = wv0 * vm2 + wv1 * vm1 + wv2 * vc + bv;
;                 f32x4 o;
; #pragma unroll
;                 for (int e = 0; e < 4; ++e) o[e] = gg[e] * pg8::sigmoid_f(gg[e]) * vv[e];
;                 u32x2 w; w.x = cvt_pk_bf16(o[0], o[1]); w.y = cvt_pk_bf16(o[2], o[3]);
;                 if (dummy) *(u32x2*)((bf16_t*)(a.ws + WS_D) + ((((size_t)(row0 + t0 + t)) * 5632 + ch) & (size_t)0x1ffffff)) = w; else *(u32x2*)(up + (size_t)(t0 + t) * 5632) = w;
;                 gm2 = gm1; gm1 = gc; vm2 = vm1; vm1 = vc; }
	v_pk_add_f32 v[246:247], v[246:247], v[238:239]
	v_rcp_f32_e32 v246, v246
	v_rcp_f32_e32 v247, v247
	v_pk_mul_f32 v[232:233], v[232:233], v[234:235]
	v_pk_mul_f32 v[232:233], v[232:233], v[246:247]
	v_cvt_pk_bf16_f32 v81, v232, v233
	v_pk_fma_f32 v[232:233], v[98:99], v[174:175], v[182:183]
	v_pk_fma_f32 v[234:235], v[86:87], v[206:207], v[214:215]
	s_nop 1
	v_fmac_f32_dpp v232, v98, v166 row_shr:1 row_mask:0xf bank_mask:0xf
	v_fmac_f32_dpp v233, v99, v167 row_shr:1 row_mask:0xf bank_mask:0xf
	v_fmac_f32_dpp v234, v86, v198 row_shr:1 row_mask:0xf bank_mask:0xf
	v_fmac_f32_dpp v235, v87, v199 row_shr:1 row_mask:0xf bank_mask:0xf
	v_fmac_f32_dpp v232, v98, v158 row_shr:2 row_mask:0xf bank_mask:0xf
	v_fmac_f32_dpp v233, v99, v159 row_shr:2 row_mask:0xf bank_mask:0xf
	v_fmac_f32_dpp v234, v86, v190 row_shr:2 row_mask:0xf bank_mask:0xf
	v_fmac_f32_dpp v235, v87, v191 row_shr:2 row_mask:0xf bank_mask:0xf
	v_fmac_f32_dpp v232, v114, v166 row_shl:15 row_mask:0xf bank_mask:0xf
	v_fmac_f32_dpp v233, v115, v167 row_shl:15 row_mask:0xf bank_mask:0xf
	v_fmac_f32_dpp v234, v102, v198 row_shl:15 row_mask:0xf bank_mask:0xf
	v_fmac_f32_dpp v235, v103, v199 row_shl:15 row_mask:0xf bank_mask:0xf
	v_fmac_f32_dpp v232, v114, v158 row_shl:14 row_mask:0xf bank_mask:0xf
	v_fmac_f32_dpp v233, v115, v159 row_shl:14 row_mask:0xf bank_mask:0xf
	v_fmac_f32_dpp v234, v102, v190 row_shl:14 row_mask:0xf bank_mask:0xf
	v_fmac_f32_dpp v235, v103, v191 row_shl:14 row_mask:0xf bank_mask:0xf
	v_mul_f32_e32 v246, v236, v232
	v_mul_f32_e32 v247, v236, v233
	v_exp_f32_e32 v246, v246
	v_exp_f32_e32 v247, v247
	s_nop 0
	v_pk_add_f32 v[246:247], v[246:247], v[238:239]
	v_rcp_f32_e32 v246, v246
	v_rcp_f32_e32 v247, v247
	v_pk_mul_f32 v[232:233], v[232:233], v[234:235]
	v_pk_mul_f32 v[232:233], v[232:233], v[246:247]
	v_cvt_pk_bf16_f32 v97, v232, v233
	v_pk_fma_f32 v[232:233], v[114:115], v[174:175], v[182:183]
	v_pk_fma_f32 v[234:235], v[102:103], v[206:207], v[214:215]
	s_nop 1
	v_fmac_f32_dpp v232, v114, v166 row_shr:1 row_mask:0xf bank_mask:0xf
	v_fmac_f32_dpp v233, v115, v167 row_shr:1 row_mask:0xf bank_mask:0xf
	v_fmac_f32_dpp v234, v102, v198 row_shr:1 row_mask:0xf bank_mask:0xf
	v_fmac_f32_dpp v235, v103, v199 row_shr:1 row_mask:0xf bank_mask:0xf
	v_fmac_f32_dpp v232, v114, v158 row_shr:2 row_mask:0xf bank_mask:0xf
	v_fmac_f32_dpp v233, v115, v159 row_shr:2 row_mask:0xf bank_mask:0xf
	v_fmac_f32_dpp v234, v102, v190 row_shr:2 row_mask:0xf bank_mask:0xf
	v_fmac_f32_dpp v235, v103, v191 row_shr:2 row_mask:0xf bank_mask:0xf
	v_fmac_f32_dpp v232, v126, v166 row_shl:15 row_mask:0xf bank_mask:0xf
	v_fmac_f32_dpp v233, v127, v167 row_shl:15 row_mask:0xf bank_mask:0xf
	v_fmac_f32_dpp v234, v118, v198 row_shl:15 row_mask:0xf bank_mask:0xf
	v_fmac_f32_dpp v235, v119, v199 row_shl:15 row_mask:0xf bank_mask:0xf
	v_fmac_f32_dpp v232, v126, v158 row_shl:14 row_mask:0xf bank_mask:0xf
	v_fmac_f32_dpp v233, v127, v159 row_shl:14 row_mask:0xf bank_mask:0xf
	v_fmac_f32_dpp v234, v118, v190 row_shl:14 row_mask:0xf bank_mask:0xf
	v_fmac_f32_dpp v235, v119, v191 row_shl:14 row_mask:0xf bank_mask:0xf
	v_mul_f32_e32 v246, v236, v232
	v_mul_f32_e32 v247, v236, v233
	v_exp_f32_e32 v246, v246
	v_exp_f32_e32 v247, v247
	s_nop 0
	v_pk_add_f32 v[246:247], v[246:247], v[238:239]
	v_rcp_f32_e32 v246, v246
	v_rcp_f32_e32 v247, v247
	v_pk_mul_f32 v[232:233], v[232:233], v[234:235]
	v_pk_mul_f32 v[232:233], v[232:233], v[246:247]
	v_cvt_pk_bf16_f32 v113, v232, v233
	v_pk_fma_f32 v[232:233], v[126:127], v[174:175], v[182:183]
	v_pk_fma_f32 v[234:235], v[118:119], v[206:207], v[214:215]
	s_nop 1
	v_fmac_f32_dpp v232, v126, v166 row_shr:1 row_mask:0xf bank_mask:0xf
	v_fmac_f32_dpp v233, v127, v167 row_shr:1 row_mask:0xf bank_mask:0xf
	v_fmac_f32_dpp v234, v118, v198 row_shr:1 row_mask:0xf bank_mask:0xf
	v_fmac_f32_dpp v235, v119, v199 row_shr:1 row_mask:0xf bank_mask:0xf
	v_fmac_f32_dpp v232, v126, v158 row_shr:2 row_mask:0xf bank_mask:0xf
	v_fmac_f32_dpp v233, v127, v159 row_shr:2 row_mask:0xf bank_mask:0xf
	v_fmac_f32_dpp v234, v118, v190 row_shr:2 row_mask:0xf bank_mask:0xf
	v_fmac_f32_dpp v235, v119, v191 row_shr:2 row_mask:0xf bank_mask:0xf
	v_mul_f32_e32 v246, v236, v232
	v_mul_f32_e32 v247, v236, v233
	v_exp_f32_e32 v246, v246
	v_exp_f32_e32 v247, v247
	s_nop 0
	v_pk_add_f32 v[246:247], v[246:247], v[238:239]
	v_rcp_f32_e32 v246, v246
	v_rcp_f32_e32 v247, v247
	v_pk_mul_f32 v[232:233], v[232:233], v[234:235]
	v_pk_mul_f32 v[232:233], v[232:233], v[246:247]
	v_cvt_pk_bf16_f32 v125, v232, v233
	v_pk_fma_f32 v[232:233], v[72:73], v[176:177], v[184:185]
	v_pk_fma_f32 v[234:235], v[64:65], v[208:209], v[216:217]
	s_nop 1
	v_fmac_f32_dpp v232, v72, v168 row_shr:1 row_mask:0xf bank_mask:0xf
	v_fmac_f32_dpp v233, v73, v169 row_shr:1 row_mask:0xf bank_mask:0xf
	v_fmac_f32_dpp v234, v64, v200 row_shr:1 row_mask:0xf bank_mask:0xf
	v_fmac_f32_dpp v235, v65, v201 row_shr:1 row_mask:0xf bank_mask:0xf
	v_fmac_f32_dpp v232, v72, v160 row_shr:2 row_mask:0xf bank_mask:0xf
	v_fmac_f32_dpp v233, v73, v161 row_shr:2 row_mask:0xf bank_mask:0xf
	v_fmac_f32_dpp v234, v64, v192 row_shr:2 row_mask:0xf bank_mask:0xf
	v_fmac_f32_dpp v235, v65, v193 row_shr:2 row_mask:0xf bank_mask:0xf
	v_fmac_f32_dpp v232, v88, v168 row_shl:15 row_mask:0xf bank_mask:0xf
	v_fmac_f32_dpp v233, v89, v169 row_shl:15 row_mask:0xf bank_mask:0xf
	v_fmac_f32_dpp v234, v76, v200 row_shl:15 row_mask:0xf bank_mask:0xf
	v_fmac_f32_dpp v235, v77, v201 row_shl:15 row_mask:0xf bank_mask:0xf
	v_fmac_f32_dpp v232, v88, v160 row_shl:14 row_mask:0xf bank_mask:0xf
	v_fmac_f32_dpp v233, v89, v161 row_shl:14 row_mask:0xf bank_mask:0xf
; __device__ __forceinline__ unsigned cvt_pk_bf16(float lo, float hi) { unsigned r; asm("v_cvt_pk_bf16_f32 %0, %1, %2" : "=v"(r) : "v"(lo), "v"(hi)); return r; }
; __device__ __forceinline__ float sigmoid_f(float v) { return __builtin_amdgcn_rcpf(1.0f + __builtin_amdgcn_exp2f(-1.4426950409f * v)); }
; __device__ __forceinline__ f32x4 bf4(u32x2 w) { return (f32x4){bf_lo(w.x), bf_hi(w.x), bf_lo(w.y), bf_hi(w.y)}; }
; __device__ __forceinline__ void phase10(const Args& a, int G, int wv, bool dummy = false) {
;     ...
;             for (int t = 0; t < 8; ++t) { const f32x4 gc = bf4(gr[t]), vc = bf4(vr[t]);
;                 const f32x4 gg = wg0 * gm2 + wg1 * gm1 + wg2 * gc + bg, vv = wv0 * vm2 + wv1 * vm1 + wv2 * vc + bv;
;                 f32x4 o;
; #pragma unroll
;                 for (int e = 0; e < 4; ++e) o[e] = gg[e] * pg8::sigmoid_f(gg[e]) * vv[e];
;                 u32x2 w; w.x = cvt_pk_bf16(o[0], o[1]); w.y = cvt_pk_bf16(o[2], o[3]);
;                 if (dummy) *(u32x2*)((bf16_t*)(a.ws + WS_D) + ((((size_t)(row0 + t0 + t)) * 5632 + ch) & (size_t)0x1ffffff)) = w; else *(u32x2*)(up + (size_t)(t0 + t) * 5632) = w;
	v_fmac_f32_dpp v234, v76, v192 row_shl:14 row_mask:0xf bank_mask:0xf
	v_fmac_f32_dpp v235, v77, v193 row_shl:14 row_mask:0xf bank_mask:0xf
	v_mul_f32_e32 v246, v236, v232
	v_mul_f32_e32 v247, v236, v233
	v_exp_f32_e32 v246, v246
	v_exp_f32_e32 v247, v247
	s_nop 0
	v_pk_add_f32 v[246:247], v[246:247], v[238:239]
	v_rcp_f32_e32 v246, v246
	v_rcp_f32_e32 v247, v247
	v_pk_mul_f32 v[232:233], v[232:233], v[234:235]
	v_pk_mul_f32 v[232:233], v[232:233], v[246:247]
	v_cvt_pk_bf16_f32 v82, v232, v233
	v_pk_fma_f32 v[232:233], v[88:89], v[176:177], v[184:185]
	v_pk_fma_f32 v[234:235], v[76:77], v[208:209], v[216:217]
	s_nop 1
	v_fmac_f32_dpp v232, v88, v168 row_shr:1 row_mask:0xf bank_mask:0xf
	v_fmac_f32_dpp v233, v89, v169 row_shr:1 row_mask:0xf bank_mask:0xf
	v_fmac_f32_dpp v234, v76, v200 row_shr:1 row_mask:0xf bank_mask:0xf
	v_fmac_f32_dpp v235, v77, v201 row_shr:1 row_mask:0xf bank_mask:0xf
	v_fmac_f32_dpp v232, v88, v160 row_shr:2 row_mask:0xf bank_mask:0xf
	v_fmac_f32_dpp v233, v89, v161 row_shr:2 row_mask:0xf bank_mask:0xf
	v_fmac_f32_dpp v234, v76, v192 row_shr:2 row_mask:0xf bank_mask:0xf
	v_fmac_f32_dpp v235, v77, v193 row_shr:2 row_mask:0xf bank_mask:0xf
	v_fmac_f32_dpp v232, v104, v168 row_shl:15 row_mask:0xf bank_mask:0xf
	v_fmac_f32_dpp v233, v105, v169 row_shl:15 row_mask:0xf bank_mask:0xf
	v_fmac_f32_dpp v234, v92, v200 row_shl:15 row_mask:0xf bank_mask:0xf
	v_fmac_f32_dpp v235, v93, v201 row_shl:15 row_mask:0xf bank_mask:0xf
	v_fmac_f32_dpp v232, v104, v160 row_shl:14 row_mask:0xf bank_mask:0xf
	v_fmac_f32_dpp v233, v105, v161 row_shl:14 row_mask:0xf bank_mask:0xf
	v_fmac_f32_dpp v234, v92, v192 row_shl:14 row_mask:0xf bank_mask:0xf
	v_fmac_f32_dpp v235, v93, v193 row_shl:14 row_mask:0xf bank_mask:0xf
	v_mul_f32_e32 v246, v236, v232
	v_mul_f32_e32 v247, v236, v233
	v_exp_f32_e32 v246, v246
	v_exp_f32_e32 v247, v247
	s_nop 0
	v_pk_add_f32 v[246:247], v[246:247], v[238:239]
	v_rcp_f32_e32 v246, v246
	v_rcp_f32_e32 v247, v247
	v_pk_mul_f32 v[232:233], v[232:233], v[234:235]
	v_pk_mul_f32 v[232:233], v[232:233], v[246:247]
	v_cvt_pk_bf16_f32 v98, v232, v233
	v_pk_fma_f32 v[232:233], v[104:105], v[176:177], v[184:185]
	v_pk_fma_f32 v[234:235], v[92:93], v[208:209], v[216:217]
	s_nop 1
	v_fmac_f32_dpp v232, v104, v168 row_shr:1 row_mask:0xf bank_mask:0xf
	v_fmac_f32_dpp v233, v105, v169 row_shr:1 row_mask:0xf bank_mask:0xf
	v_fmac_f32_dpp v234, v92, v200 row_shr:1 row_mask:0xf bank_mask:0xf
	v_fmac_f32_dpp v235, v93, v201 row_shr:1 row_mask:0xf bank_mask:0xf
	v_fmac_f32_dpp v232, v104, v160 row_shr:2 row_mask:0xf bank_mask:0xf
	v_fmac_f32_dpp v233, v105, v161 row_shr:2 row_mask:0xf bank_mask:0xf
	v_fmac_f32_dpp v234, v92, v192 row_shr:2 row_mask:0xf bank_mask:0xf
	v_fmac_f32_dpp v235, v93, v193 row_shr:2 row_mask:0xf bank_mask:0xf
	v_fmac_f32_dpp v232, v120, v168 row_shl:15 row_mask:0xf bank_mask:0xf
	v_fmac_f32_dpp v233, v121, v169 row_shl:15 row_mask:0xf bank_mask:0xf
	v_fmac_f32_dpp v234, v108, v200 row_shl:15 row_mask:0xf bank_mask:0xf
	v_fmac_f32_dpp v235, v109, v201 row_shl:15 row_mask:0xf bank_mask:0xf
	v_fmac_f32_dpp v232, v120, v160 row_shl:14 row_mask:0xf bank_mask:0xf
	v_fmac_f32_dpp v233, v121, v161 row_shl:14 row_mask:0xf bank_mask:0xf
	v_fmac_f32_dpp v234, v108, v192 row_shl:14 row_mask:0xf bank_mask:0xf
	v_fmac_f32_dpp v235, v109, v193 row_shl:14 row_mask:0xf bank_mask:0xf
	v_mul_f32_e32 v246, v236, v232
	v_mul_f32_e32 v247, v236, v233
	v_exp_f32_e32 v246, v246
	v_exp_f32_e32 v247, v247
	s_nop 0
	v_pk_add_f32 v[246:247], v[246:247], v[238:239]
	v_rcp_f32_e32 v246, v246
	v_rcp_f32_e32 v247, v247
	v_pk_mul_f32 v[232:233], v[232:233], v[234:235]
	v_pk_mul_f32 v[232:233], v[232:233], v[246:247]
	v_cvt_pk_bf16_f32 v114, v232, v233
	v_pk_fma_f32 v[232:233], v[120:121], v[176:177], v[184:185]
	v_pk_fma_f32 v[234:235], v[108:109], v[208:209], v[216:217]
	s_nop 1
	v_fmac_f32_dpp v232, v120, v168 row_shr:1 row_mask:0xf bank_mask:0xf
	v_fmac_f32_dpp v233, v121, v169 row_shr:1 row_mask:0xf bank_mask:0xf
	v_fmac_f32_dpp v234, v108, v200 row_shr:1 row_mask:0xf bank_mask:0xf
	v_fmac_f32_dpp v235, v109, v201 row_shr:1 row_mask:0xf bank_mask:0xf
	v_fmac_f32_dpp v232, v120, v160 row_shr:2 row_mask:0xf bank_mask:0xf
	v_fmac_f32_dpp v233, v121, v161 row_shr:2 row_mask:0xf bank_mask:0xf
	v_fmac_f32_dpp v234, v108, v192 row_shr:2 row_mask:0xf bank_mask:0xf
	v_fmac_f32_dpp v235, v109, v193 row_shr:2 row_mask:0xf bank_mask:0xf
	v_mul_f32_e32 v246, v236, v232
	v_mul_f32_e32 v247, v236, v233
	v_exp_f32_e32 v246, v246
	v_exp_f32_e32 v247, v247
	s_nop 0
	v_pk_add_f32 v[246:247], v[246:247], v[238:239]
	v_rcp_f32_e32 v246, v246
	v_rcp_f32_e32 v247, v247
	v_pk_mul_f32 v[232:233], v[232:233], v[234:235]
	v_pk_mul_f32 v[232:233], v[232:233], v[246:247]
	v_cvt_pk_bf16_f32 v126, v232, v233
	v_pk_fma_f32 v[232:233], v[74:75], v[178:179], v[186:187]
	v_pk_fma_f32 v[234:235], v[66:67], v[210:211], v[218:219]
	s_nop 1
	v_fmac_f32_dpp v232, v74, v170 row_shr:1 row_mask:0xf bank_mask:0xf
	v_fmac_f32_dpp v233, v75, v171 row_shr:1 row_mask:0xf bank_mask:0xf
	v_fmac_f32_dpp v234, v66, v202 row_shr:1 row_mask:0xf bank_mask:0xf
	v_fmac_f32_dpp v235, v67, v203 row_shr:1 row_mask:0xf bank_mask:0xf
	v_fmac_f32_dpp v232, v74, v162 row_shr:2 row_mask:0xf bank_mask:0xf
	v_fmac_f32_dpp v233, v75, v163 row_shr:2 row_mask:0xf bank_mask:0xf
	v_fmac_f32_dpp v234, v66, v194 row_shr:2 row_mask:0xf bank_mask:0xf
	v_fmac_f32_dpp v235, v67, v195 row_shr:2 row_mask:0xf bank_mask:0xf
	v_fmac_f32_dpp v232, v90, v170 row_shl:15 row_mask:0xf bank_mask:0xf
	v_fmac_f32_dpp v233, v91, v171 row_shl:15 row_mask:0xf bank_mask:0xf
	v_fmac_f32_dpp v234, v78, v202 row_shl:15 row_mask:0xf bank_mask:0xf
; __device__ __forceinline__ unsigned cvt_pk_bf16(float lo, float hi) { unsigned r; asm("v_cvt_pk_bf16_f32 %0, %1, %2" : "=v"(r) : "v"(lo), "v"(hi)); return r; }
; __device__ __forceinline__ float sigmoid_f(float v) { return __builtin_amdgcn_rcpf(1.0f + __builtin_amdgcn_exp2f(-1.4426950409f * v)); }
; __device__ __forceinline__ u32x4 pack8(f32x4 a, f32x4 b) { u32x4 w; w.x = cvt_pk_bf16(a[0], a[1]); w.y = cvt_pk_bf16(a[2], a[3]); w.z = cvt_pk_bf16(b[0], b[1]); w.w = cvt_pk_bf16(b[2], b[3]); return w; }
; __device__ __forceinline__ f32x4 bf4(u32x2 w) { return (f32x4){bf_lo(w.x), bf_hi(w.x), bf_lo(w.y), bf_hi(w.y)}; }
;     __device__ __forceinline__ void operator()(const f32x4 (&acc)[2][2][4][2], const Unit& u, int wr, int wc, int fr, int fq) const {
;     ...
;             for (int m = 0; m < 4; ++m) { const int row = row0 + ai * HALF + m * 16; bf16_t* rowp = UP + (size_t)row * 5632 + u.pn * HALF + wc * 32 + 8 * fq;
; #pragma unroll
;                 for (int bj = 0; bj < 2; ++bj) { const u32x4 w = pack8(acc[ai][bj][m][0], acc[ai][bj][m][1]); __builtin_nontemporal_store(w, (u32x4*)(rowp + (size_t)bj * ((size_t)16384 * 5632)));
; __device__ __forceinline__ void phase10(const Args& a, int G, int wv, bool dummy = false) {
;     ...
;             for (int t = 0; t < 8; ++t) { const f32x4 gc = bf4(gr[t]), vc = bf4(vr[t]);
;                 const f32x4 gg = wg0 * gm2 + wg1 * gm1 + wg2 * gc + bg, vv = wv0 * vm2 + wv1 * vm1 + wv2 * vc + bv;
;                 f32x4 o;
; #pragma unroll
;                 for (int e = 0; e < 4; ++e) o[e] = gg[e] * pg8::sigmoid_f(gg[e]) * vv[e];
;                 u32x2 w; w.x = cvt_pk_bf16(o[0], o[1]); w.y = cvt_pk_bf16(o[2], o[3]);
;                 if (dummy) *(u32x2*)((bf16_t*)(a.ws + WS_D) + ((((size_t)(row0 + t0 + t)) * 5632 + ch) & (size_t)0x1ffffff)) = w; else *(u32x2*)(up + (size_t)(t0 + t) * 5632) = w;
	v_fmac_f32_dpp v235, v79, v203 row_shl:15 row_mask:0xf bank_mask:0xf
	v_fmac_f32_dpp v232, v90, v162 row_shl:14 row_mask:0xf bank_mask:0xf
	v_fmac_f32_dpp v233, v91, v163 row_shl:14 row_mask:0xf bank_mask:0xf
	v_fmac_f32_dpp v234, v78, v194 row_shl:14 row_mask:0xf bank_mask:0xf
	v_fmac_f32_dpp v235, v79, v195 row_shl:14 row_mask:0xf bank_mask:0xf
	v_mul_f32_e32 v246, v236, v232
	v_mul_f32_e32 v247, v236, v233
	v_exp_f32_e32 v246, v246
	v_exp_f32_e32 v247, v247
	s_nop 0
	v_pk_add_f32 v[246:247], v[246:247], v[238:239]
	v_rcp_f32_e32 v246, v246
	v_rcp_f32_e32 v247, v247
	v_pk_mul_f32 v[232:233], v[232:233], v[234:235]
	v_pk_mul_f32 v[232:233], v[232:233], v[246:247]
	v_cvt_pk_bf16_f32 v83, v232, v233
	v_pk_fma_f32 v[232:233], v[90:91], v[178:179], v[186:187]
	v_pk_fma_f32 v[234:235], v[78:79], v[210:211], v[218:219]
	s_nop 1
	v_fmac_f32_dpp v232, v90, v170 row_shr:1 row_mask:0xf bank_mask:0xf
	v_fmac_f32_dpp v233, v91, v171 row_shr:1 row_mask:0xf bank_mask:0xf
	v_fmac_f32_dpp v234, v78, v202 row_shr:1 row_mask:0xf bank_mask:0xf
	v_fmac_f32_dpp v235, v79, v203 row_shr:1 row_mask:0xf bank_mask:0xf
	v_fmac_f32_dpp v232, v90, v162 row_shr:2 row_mask:0xf bank_mask:0xf
	v_fmac_f32_dpp v233, v91, v163 row_shr:2 row_mask:0xf bank_mask:0xf
	v_fmac_f32_dpp v234, v78, v194 row_shr:2 row_mask:0xf bank_mask:0xf
	v_fmac_f32_dpp v235, v79, v195 row_shr:2 row_mask:0xf bank_mask:0xf
	v_fmac_f32_dpp v232, v106, v170 row_shl:15 row_mask:0xf bank_mask:0xf
	v_fmac_f32_dpp v233, v107, v171 row_shl:15 row_mask:0xf bank_mask:0xf
	v_fmac_f32_dpp v234, v94, v202 row_shl:15 row_mask:0xf bank_mask:0xf
	v_fmac_f32_dpp v235, v95, v203 row_shl:15 row_mask:0xf bank_mask:0xf
	v_fmac_f32_dpp v232, v106, v162 row_shl:14 row_mask:0xf bank_mask:0xf
	v_fmac_f32_dpp v233, v107, v163 row_shl:14 row_mask:0xf bank_mask:0xf
	v_fmac_f32_dpp v234, v94, v194 row_shl:14 row_mask:0xf bank_mask:0xf
	v_fmac_f32_dpp v235, v95, v195 row_shl:14 row_mask:0xf bank_mask:0xf
	v_mul_f32_e32 v246, v236, v232
	v_mul_f32_e32 v247, v236, v233
	v_exp_f32_e32 v246, v246
	v_exp_f32_e32 v247, v247
	s_nop 0
	v_pk_add_f32 v[246:247], v[246:247], v[238:239]
	v_rcp_f32_e32 v246, v246
	v_rcp_f32_e32 v247, v247
	v_pk_mul_f32 v[232:233], v[232:233], v[234:235]
	v_pk_mul_f32 v[232:233], v[232:233], v[246:247]
	v_cvt_pk_bf16_f32 v99, v232, v233
	v_pk_fma_f32 v[232:233], v[106:107], v[178:179], v[186:187]
	v_pk_fma_f32 v[234:235], v[94:95], v[210:211], v[218:219]
	s_nop 1
	v_fmac_f32_dpp v232, v106, v170 row_shr:1 row_mask:0xf bank_mask:0xf
	v_fmac_f32_dpp v233, v107, v171 row_shr:1 row_mask:0xf bank_mask:0xf
	v_fmac_f32_dpp v234, v94, v202 row_shr:1 row_mask:0xf bank_mask:0xf
	v_fmac_f32_dpp v235, v95, v203 row_shr:1 row_mask:0xf bank_mask:0xf
	v_fmac_f32_dpp v232, v106, v162 row_shr:2 row_mask:0xf bank_mask:0xf
	v_fmac_f32_dpp v233, v107, v163 row_shr:2 row_mask:0xf bank_mask:0xf
	v_fmac_f32_dpp v234, v94, v194 row_shr:2 row_mask:0xf bank_mask:0xf
	v_fmac_f32_dpp v235, v95, v195 row_shr:2 row_mask:0xf bank_mask:0xf
	v_fmac_f32_dpp v232, v122, v170 row_shl:15 row_mask:0xf bank_mask:0xf
	v_fmac_f32_dpp v233, v123, v171 row_shl:15 row_mask:0xf bank_mask:0xf
	v_fmac_f32_dpp v234, v110, v202 row_shl:15 row_mask:0xf bank_mask:0xf
	v_fmac_f32_dpp v235, v111, v203 row_shl:15 row_mask:0xf bank_mask:0xf
	v_fmac_f32_dpp v232, v122, v162 row_shl:14 row_mask:0xf bank_mask:0xf
	v_fmac_f32_dpp v233, v123, v163 row_shl:14 row_mask:0xf bank_mask:0xf
	v_fmac_f32_dpp v234, v110, v194 row_shl:14 row_mask:0xf bank_mask:0xf
	v_fmac_f32_dpp v235, v111, v195 row_shl:14 row_mask:0xf bank_mask:0xf
	v_mul_f32_e32 v246, v236, v232
	v_mul_f32_e32 v247, v236, v233
	v_exp_f32_e32 v246, v246
	v_exp_f32_e32 v247, v247
	s_nop 0
	v_pk_add_f32 v[246:247], v[246:247], v[238:239]
	v_rcp_f32_e32 v246, v246
	v_rcp_f32_e32 v247, v247
	v_pk_mul_f32 v[232:233], v[232:233], v[234:235]
	v_pk_mul_f32 v[232:233], v[232:233], v[246:247]
	v_cvt_pk_bf16_f32 v115, v232, v233
	v_pk_fma_f32 v[232:233], v[122:123], v[178:179], v[186:187]
	v_pk_fma_f32 v[234:235], v[110:111], v[210:211], v[218:219]
	s_nop 1
	v_fmac_f32_dpp v232, v122, v170 row_shr:1 row_mask:0xf bank_mask:0xf
	v_fmac_f32_dpp v233, v123, v171 row_shr:1 row_mask:0xf bank_mask:0xf
	v_fmac_f32_dpp v234, v110, v202 row_shr:1 row_mask:0xf bank_mask:0xf
	v_fmac_f32_dpp v235, v111, v203 row_shr:1 row_mask:0xf bank_mask:0xf
	v_fmac_f32_dpp v232, v122, v162 row_shr:2 row_mask:0xf bank_mask:0xf
	v_fmac_f32_dpp v233, v123, v163 row_shr:2 row_mask:0xf bank_mask:0xf
	v_fmac_f32_dpp v234, v110, v194 row_shr:2 row_mask:0xf bank_mask:0xf
	v_fmac_f32_dpp v235, v111, v195 row_shr:2 row_mask:0xf bank_mask:0xf
	v_mul_f32_e32 v246, v236, v232
	v_mul_f32_e32 v247, v236, v233
	v_exp_f32_e32 v246, v246
	v_exp_f32_e32 v247, v247
	s_nop 0
	v_pk_add_f32 v[246:247], v[246:247], v[238:239]
	v_rcp_f32_e32 v246, v246
	v_rcp_f32_e32 v247, v247
	v_pk_mul_f32 v[232:233], v[232:233], v[234:235]
	v_pk_mul_f32 v[232:233], v[232:233], v[246:247]
	v_cvt_pk_bf16_f32 v127, v232, v233
	s_andn2_b64 exec, exec, s[64:65]
	global_store_dwordx4 v149, v[124:127], s[100:101]
	s_mov_b64 exec, -1
	s_add_u32 s36, s100, 0x2c000
	s_addc_u32 s37, s101, 0
	global_store_dwordx4 v149, v[112:115], s[36:37]
	s_add_u32 s36, s100, 0x58000
	s_addc_u32 s37, s101, 0
	global_store_dwordx4 v149, v[96:99], s[36:37]
	s_add_u32 s36, s100, 0x84000
	s_addc_u32 s37, s101, 0
	global_store_dwordx4 v149, v[80:83], s[36:37]
	s_nop 4
	v_pk_fma_f32 v[232:233], v[16:17], v[172:173], v[180:181]
	v_pk_fma_f32 v[234:235], v[4:5], v[204:205], v[212:213]
	s_nop 1
	v_fmac_f32_dpp v232, v16, v164 row_shr:1 row_mask:0xf bank_mask:0xf
	v_fmac_f32_dpp v233, v17, v165 row_shr:1 row_mask:0xf bank_mask:0xf
; __device__ __forceinline__ unsigned cvt_pk_bf16(float lo, float hi) { unsigned r; asm("v_cvt_pk_bf16_f32 %0, %1, %2" : "=v"(r) : "v"(lo), "v"(hi)); return r; }
; __device__ __forceinline__ float sigmoid_f(float v) { return __builtin_amdgcn_rcpf(1.0f + __builtin_amdgcn_exp2f(-1.4426950409f * v)); }
; __device__ __forceinline__ f32x4 bf4(u32x2 w) { return (f32x4){bf_lo(w.x), bf_hi(w.x), bf_lo(w.y), bf_hi(w.y)}; }
; __device__ __forceinline__ void phase10(const Args& a, int G, int wv, bool dummy = false) {
;     ...
;             for (int t = 0; t < 8; ++t) { const f32x4 gc = bf4(gr[t]), vc = bf4(vr[t]);
;                 const f32x4 gg = wg0 * gm2 + wg1 * gm1 + wg2 * gc + bg, vv = wv0 * vm2 + wv1 * vm1 + wv2 * vc + bv;
;                 f32x4 o;
; #pragma unroll
;                 for (int e = 0; e < 4; ++e) o[e] = gg[e] * pg8::sigmoid_f(gg[e]) * vv[e];
;                 u32x2 w; w.x = cvt_pk_bf16(o[0], o[1]); w.y = cvt_pk_bf16(o[2], o[3]);
;                 if (dummy) *(u32x2*)((bf16_t*)(a.ws + WS_D) + ((((size_t)(row0 + t0 + t)) * 5632 + ch) & (size_t)0x1ffffff)) = w; else *(u32x2*)(up + (size_t)(t0 + t) * 5632) = w;
	v_fmac_f32_dpp v234, v4, v196 row_shr:1 row_mask:0xf bank_mask:0xf
	v_fmac_f32_dpp v235, v5, v197 row_shr:1 row_mask:0xf bank_mask:0xf
	v_fmac_f32_dpp v232, v16, v156 row_shr:2 row_mask:0xf bank_mask:0xf
	v_fmac_f32_dpp v233, v17, v157 row_shr:2 row_mask:0xf bank_mask:0xf
	v_fmac_f32_dpp v234, v4, v188 row_shr:2 row_mask:0xf bank_mask:0xf
	v_fmac_f32_dpp v235, v5, v189 row_shr:2 row_mask:0xf bank_mask:0xf
	v_fmac_f32_dpp v232, v32, v164 row_shl:15 row_mask:0xf bank_mask:0xf
	v_fmac_f32_dpp v233, v33, v165 row_shl:15 row_mask:0xf bank_mask:0xf
	v_fmac_f32_dpp v234, v20, v196 row_shl:15 row_mask:0xf bank_mask:0xf
	v_fmac_f32_dpp v235, v21, v197 row_shl:15 row_mask:0xf bank_mask:0xf
	v_fmac_f32_dpp v232, v32, v156 row_shl:14 row_mask:0xf bank_mask:0xf
	v_fmac_f32_dpp v233, v33, v157 row_shl:14 row_mask:0xf bank_mask:0xf
	v_fmac_f32_dpp v234, v20, v188 row_shl:14 row_mask:0xf bank_mask:0xf
	v_fmac_f32_dpp v235, v21, v189 row_shl:14 row_mask:0xf bank_mask:0xf
	v_mul_f32_e32 v246, v236, v232
	v_mul_f32_e32 v247, v236, v233
	v_exp_f32_e32 v246, v246
	v_exp_f32_e32 v247, v247
	s_nop 0
	v_pk_add_f32 v[246:247], v[246:247], v[238:239]
	v_rcp_f32_e32 v246, v246
	v_rcp_f32_e32 v247, v247
	v_pk_mul_f32 v[232:233], v[232:233], v[234:235]
	v_pk_mul_f32 v[232:233], v[232:233], v[246:247]
	v_cvt_pk_bf16_f32 v16, v232, v233
	v_pk_fma_f32 v[232:233], v[32:33], v[172:173], v[180:181]
	v_pk_fma_f32 v[234:235], v[20:21], v[204:205], v[212:213]
	s_nop 1
	v_fmac_f32_dpp v232, v32, v164 row_shr:1 row_mask:0xf bank_mask:0xf
	v_fmac_f32_dpp v233, v33, v165 row_shr:1 row_mask:0xf bank_mask:0xf
	v_fmac_f32_dpp v234, v20, v196 row_shr:1 row_mask:0xf bank_mask:0xf
	v_fmac_f32_dpp v235, v21, v197 row_shr:1 row_mask:0xf bank_mask:0xf
	v_fmac_f32_dpp v232, v32, v156 row_shr:2 row_mask:0xf bank_mask:0xf
	v_fmac_f32_dpp v233, v33, v157 row_shr:2 row_mask:0xf bank_mask:0xf
	v_fmac_f32_dpp v234, v20, v188 row_shr:2 row_mask:0xf bank_mask:0xf
	v_fmac_f32_dpp v235, v21, v189 row_shr:2 row_mask:0xf bank_mask:0xf
	v_fmac_f32_dpp v232, v48, v164 row_shl:15 row_mask:0xf bank_mask:0xf
	v_fmac_f32_dpp v233, v49, v165 row_shl:15 row_mask:0xf bank_mask:0xf
	v_fmac_f32_dpp v234, v36, v196 row_shl:15 row_mask:0xf bank_mask:0xf
	v_fmac_f32_dpp v235, v37, v197 row_shl:15 row_mask:0xf bank_mask:0xf
	v_fmac_f32_dpp v232, v48, v156 row_shl:14 row_mask:0xf bank_mask:0xf
	v_fmac_f32_dpp v233, v49, v157 row_shl:14 row_mask:0xf bank_mask:0xf
	v_fmac_f32_dpp v234, v36, v188 row_shl:14 row_mask:0xf bank_mask:0xf
	v_fmac_f32_dpp v235, v37, v189 row_shl:14 row_mask:0xf bank_mask:0xf
	v_mul_f32_e32 v246, v236, v232
	v_mul_f32_e32 v247, v236, v233
	v_exp_f32_e32 v246, v246
	v_exp_f32_e32 v247, v247
	s_nop 0
	v_pk_add_f32 v[246:247], v[246:247], v[238:239]
	v_rcp_f32_e32 v246, v246
	v_rcp_f32_e32 v247, v247
	v_pk_mul_f32 v[232:233], v[232:233], v[234:235]
	v_pk_mul_f32 v[232:233], v[232:233], v[246:247]
	v_cvt_pk_bf16_f32 v32, v232, v233
	v_pk_fma_f32 v[232:233], v[48:49], v[172:173], v[180:181]
	v_pk_fma_f32 v[234:235], v[36:37], v[204:205], v[212:213]
	s_nop 1
	v_fmac_f32_dpp v232, v48, v164 row_shr:1 row_mask:0xf bank_mask:0xf
	v_fmac_f32_dpp v233, v49, v165 row_shr:1 row_mask:0xf bank_mask:0xf
	v_fmac_f32_dpp v234, v36, v196 row_shr:1 row_mask:0xf bank_mask:0xf
	v_fmac_f32_dpp v235, v37, v197 row_shr:1 row_mask:0xf bank_mask:0xf
	v_fmac_f32_dpp v232, v48, v156 row_shr:2 row_mask:0xf bank_mask:0xf
	v_fmac_f32_dpp v233, v49, v157 row_shr:2 row_mask:0xf bank_mask:0xf
	v_fmac_f32_dpp v234, v36, v188 row_shr:2 row_mask:0xf bank_mask:0xf
	v_fmac_f32_dpp v235, v37, v189 row_shr:2 row_mask:0xf bank_mask:0xf
	v_fmac_f32_dpp v232, v60, v164 row_shl:15 row_mask:0xf bank_mask:0xf
	v_fmac_f32_dpp v233, v61, v165 row_shl:15 row_mask:0xf bank_mask:0xf
	v_fmac_f32_dpp v234, v52, v196 row_shl:15 row_mask:0xf bank_mask:0xf
	v_fmac_f32_dpp v235, v53, v197 row_shl:15 row_mask:0xf bank_mask:0xf
	v_fmac_f32_dpp v232, v60, v156 row_shl:14 row_mask:0xf bank_mask:0xf
	v_fmac_f32_dpp v233, v61, v157 row_shl:14 row_mask:0xf bank_mask:0xf
	v_fmac_f32_dpp v234, v52, v188 row_shl:14 row_mask:0xf bank_mask:0xf
	v_fmac_f32_dpp v235, v53, v189 row_shl:14 row_mask:0xf bank_mask:0xf
	v_mul_f32_e32 v246, v236, v232
	v_mul_f32_e32 v247, v236, v233
	v_exp_f32_e32 v246, v246
	v_exp_f32_e32 v247, v247
	s_nop 0
	v_pk_add_f32 v[246:247], v[246:247], v[238:239]
	v_rcp_f32_e32 v246, v246
	v_rcp_f32_e32 v247, v247
	v_pk_mul_f32 v[232:233], v[232:233], v[234:235]
	v_pk_mul_f32 v[232:233], v[232:233], v[246:247]
	v_cvt_pk_bf16_f32 v48, v232, v233
	v_pk_fma_f32 v[232:233], v[60:61], v[172:173], v[180:181]
	v_pk_fma_f32 v[234:235], v[52:53], v[204:205], v[212:213]
	s_nop 1
	v_fmac_f32_dpp v232, v60, v164 row_shr:1 row_mask:0xf bank_mask:0xf
	v_fmac_f32_dpp v233, v61, v165 row_shr:1 row_mask:0xf bank_mask:0xf
	v_fmac_f32_dpp v234, v52, v196 row_shr:1 row_mask:0xf bank_mask:0xf
	v_fmac_f32_dpp v235, v53, v197 row_shr:1 row_mask:0xf bank_mask:0xf
	v_fmac_f32_dpp v232, v60, v156 row_shr:2 row_mask:0xf bank_mask:0xf
	v_fmac_f32_dpp v233, v61, v157 row_shr:2 row_mask:0xf bank_mask:0xf
	v_fmac_f32_dpp v234, v52, v188 row_shr:2 row_mask:0xf bank_mask:0xf
	v_fmac_f32_dpp v235, v53, v189 row_shr:2 row_mask:0xf bank_mask:0xf
	v_mul_f32_e32 v246, v236, v232
	v_mul_f32_e32 v247, v236, v233
	v_exp_f32_e32 v246, v246
	v_exp_f32_e32 v247, v247
	s_nop 0
	v_pk_add_f32 v[246:247], v[246:247], v[238:239]
	v_rcp_f32_e32 v246, v246
	v_rcp_f32_e32 v247, v247
	v_pk_mul_f32 v[232:233], v[232:233], v[234:235]
	v_pk_mul_f32 v[232:233], v[232:233], v[246:247]
	v_cvt_pk_bf16_f32 v60, v232, v233
	v_pk_fma_f32 v[232:233], v[18:19], v[174:175], v[182:183]
; __device__ __forceinline__ unsigned cvt_pk_bf16(float lo, float hi) { unsigned r; asm("v_cvt_pk_bf16_f32 %0, %1, %2" : "=v"(r) : "v"(lo), "v"(hi)); return r; }
; __device__ __forceinline__ float sigmoid_f(float v) { return __builtin_amdgcn_rcpf(1.0f + __builtin_amdgcn_exp2f(-1.4426950409f * v)); }
; __device__ __forceinline__ f32x4 bf4(u32x2 w) { return (f32x4){bf_lo(w.x), bf_hi(w.x), bf_lo(w.y), bf_hi(w.y)}; }
; __device__ __forceinline__ void phase10(const Args& a, int G, int wv, bool dummy = false) {
;     ...
;             for (int t = 0; t < 8; ++t) { const f32x4 gc = bf4(gr[t]), vc = bf4(vr[t]);
;                 const f32x4 gg = wg0 * gm2 + wg1 * gm1 + wg2 * gc + bg, vv = wv0 * vm2 + wv1 * vm1 + wv2 * vc + bv;
;                 f32x4 o;
; #pragma unroll
;                 for (int e = 0; e < 4; ++e) o[e] = gg[e] * pg8::sigmoid_f(gg[e]) * vv[e];
;                 u32x2 w; w.x = cvt_pk_bf16(o[0], o[1]); w.y = cvt_pk_bf16(o[2], o[3]);
;                 if (dummy) *(u32x2*)((bf16_t*)(a.ws + WS_D) + ((((size_t)(row0 + t0 + t)) * 5632 + ch) & (size_t)0x1ffffff)) = w; else *(u32x2*)(up + (size_t)(t0 + t) * 5632) = w;
	v_pk_fma_f32 v[234:235], v[6:7], v[206:207], v[214:215]
	s_nop 1
	v_fmac_f32_dpp v232, v18, v166 row_shr:1 row_mask:0xf bank_mask:0xf
	v_fmac_f32_dpp v233, v19, v167 row_shr:1 row_mask:0xf bank_mask:0xf
	v_fmac_f32_dpp v234, v6, v198 row_shr:1 row_mask:0xf bank_mask:0xf
	v_fmac_f32_dpp v235, v7, v199 row_shr:1 row_mask:0xf bank_mask:0xf
	v_fmac_f32_dpp v232, v18, v158 row_shr:2 row_mask:0xf bank_mask:0xf
	v_fmac_f32_dpp v233, v19, v159 row_shr:2 row_mask:0xf bank_mask:0xf
	v_fmac_f32_dpp v234, v6, v190 row_shr:2 row_mask:0xf bank_mask:0xf
	v_fmac_f32_dpp v235, v7, v191 row_shr:2 row_mask:0xf bank_mask:0xf
	v_fmac_f32_dpp v232, v34, v166 row_shl:15 row_mask:0xf bank_mask:0xf
	v_fmac_f32_dpp v233, v35, v167 row_shl:15 row_mask:0xf bank_mask:0xf
	v_fmac_f32_dpp v234, v22, v198 row_shl:15 row_mask:0xf bank_mask:0xf
	v_fmac_f32_dpp v235, v23, v199 row_shl:15 row_mask:0xf bank_mask:0xf
	v_fmac_f32_dpp v232, v34, v158 row_shl:14 row_mask:0xf bank_mask:0xf
	v_fmac_f32_dpp v233, v35, v159 row_shl:14 row_mask:0xf bank_mask:0xf
	v_fmac_f32_dpp v234, v22, v190 row_shl:14 row_mask:0xf bank_mask:0xf
	v_fmac_f32_dpp v235, v23, v191 row_shl:14 row_mask:0xf bank_mask:0xf
	v_mul_f32_e32 v246, v236, v232
	v_mul_f32_e32 v247, v236, v233
	v_exp_f32_e32 v246, v246
	v_exp_f32_e32 v247, v247
	s_nop 0
	v_pk_add_f32 v[246:247], v[246:247], v[238:239]
	v_rcp_f32_e32 v246, v246
	v_rcp_f32_e32 v247, v247
	v_pk_mul_f32 v[232:233], v[232:233], v[234:235]
	v_pk_mul_f32 v[232:233], v[232:233], v[246:247]
	v_cvt_pk_bf16_f32 v17, v232, v233
	v_pk_fma_f32 v[232:233], v[34:35], v[174:175], v[182:183]
	v_pk_fma_f32 v[234:235], v[22:23], v[206:207], v[214:215]
	s_nop 1
	v_fmac_f32_dpp v232, v34, v166 row_shr:1 row_mask:0xf bank_mask:0xf
	v_fmac_f32_dpp v233, v35, v167 row_shr:1 row_mask:0xf bank_mask:0xf
	v_fmac_f32_dpp v234, v22, v198 row_shr:1 row_mask:0xf bank_mask:0xf
	v_fmac_f32_dpp v235, v23, v199 row_shr:1 row_mask:0xf bank_mask:0xf
	v_fmac_f32_dpp v232, v34, v158 row_shr:2 row_mask:0xf bank_mask:0xf
	v_fmac_f32_dpp v233, v35, v159 row_shr:2 row_mask:0xf bank_mask:0xf
	v_fmac_f32_dpp v234, v22, v190 row_shr:2 row_mask:0xf bank_mask:0xf
	v_fmac_f32_dpp v235, v23, v191 row_shr:2 row_mask:0xf bank_mask:0xf
	v_fmac_f32_dpp v232, v50, v166 row_shl:15 row_mask:0xf bank_mask:0xf
	v_fmac_f32_dpp v233, v51, v167 row_shl:15 row_mask:0xf bank_mask:0xf
	v_fmac_f32_dpp v234, v38, v198 row_shl:15 row_mask:0xf bank_mask:0xf
	v_fmac_f32_dpp v235, v39, v199 row_shl:15 row_mask:0xf bank_mask:0xf
	v_fmac_f32_dpp v232, v50, v158 row_shl:14 row_mask:0xf bank_mask:0xf
	v_fmac_f32_dpp v233, v51, v159 row_shl:14 row_mask:0xf bank_mask:0xf
	v_fmac_f32_dpp v234, v38, v190 row_shl:14 row_mask:0xf bank_mask:0xf
	v_fmac_f32_dpp v235, v39, v191 row_shl:14 row_mask:0xf bank_mask:0xf
	v_mul_f32_e32 v246, v236, v232
	v_mul_f32_e32 v247, v236, v233
	v_exp_f32_e32 v246, v246
	v_exp_f32_e32 v247, v247
	s_nop 0
	v_pk_add_f32 v[246:247], v[246:247], v[238:239]
	v_rcp_f32_e32 v246, v246
	v_rcp_f32_e32 v247, v247
	v_pk_mul_f32 v[232:233], v[232:233], v[234:235]
	v_pk_mul_f32 v[232:233], v[232:233], v[246:247]
	v_cvt_pk_bf16_f32 v33, v232, v233
	v_pk_fma_f32 v[232:233], v[50:51], v[174:175], v[182:183]
	v_pk_fma_f32 v[234:235], v[38:39], v[206:207], v[214:215]
	s_nop 1
	v_fmac_f32_dpp v232, v50, v166 row_shr:1 row_mask:0xf bank_mask:0xf
	v_fmac_f32_dpp v233, v51, v167 row_shr:1 row_mask:0xf bank_mask:0xf
	v_fmac_f32_dpp v234, v38, v198 row_shr:1 row_mask:0xf bank_mask:0xf
	v_fmac_f32_dpp v235, v39, v199 row_shr:1 row_mask:0xf bank_mask:0xf
	v_fmac_f32_dpp v232, v50, v158 row_shr:2 row_mask:0xf bank_mask:0xf
	v_fmac_f32_dpp v233, v51, v159 row_shr:2 row_mask:0xf bank_mask:0xf
	v_fmac_f32_dpp v234, v38, v190 row_shr:2 row_mask:0xf bank_mask:0xf
	v_fmac_f32_dpp v235, v39, v191 row_shr:2 row_mask:0xf bank_mask:0xf
	v_fmac_f32_dpp v232, v62, v166 row_shl:15 row_mask:0xf bank_mask:0xf
	v_fmac_f32_dpp v233, v63, v167 row_shl:15 row_mask:0xf bank_mask:0xf
	v_fmac_f32_dpp v234, v54, v198 row_shl:15 row_mask:0xf bank_mask:0xf
	v_fmac_f32_dpp v235, v55, v199 row_shl:15 row_mask:0xf bank_mask:0xf
	v_fmac_f32_dpp v232, v62, v158 row_shl:14 row_mask:0xf bank_mask:0xf
	v_fmac_f32_dpp v233, v63, v159 row_shl:14 row_mask:0xf bank_mask:0xf
	v_fmac_f32_dpp v234, v54, v190 row_shl:14 row_mask:0xf bank_mask:0xf
	v_fmac_f32_dpp v235, v55, v191 row_shl:14 row_mask:0xf bank_mask:0xf
	v_mul_f32_e32 v246, v236, v232
	v_mul_f32_e32 v247, v236, v233
	v_exp_f32_e32 v246, v246
	v_exp_f32_e32 v247, v247
	s_nop 0
	v_pk_add_f32 v[246:247], v[246:247], v[238:239]
	v_rcp_f32_e32 v246, v246
	v_rcp_f32_e32 v247, v247
	v_pk_mul_f32 v[232:233], v[232:233], v[234:235]
	v_pk_mul_f32 v[232:233], v[232:233], v[246:247]
	v_cvt_pk_bf16_f32 v49, v232, v233
	v_pk_fma_f32 v[232:233], v[62:63], v[174:175], v[182:183]
	v_pk_fma_f32 v[234:235], v[54:55], v[206:207], v[214:215]
	s_nop 1
	v_fmac_f32_dpp v232, v62, v166 row_shr:1 row_mask:0xf bank_mask:0xf
	v_fmac_f32_dpp v233, v63, v167 row_shr:1 row_mask:0xf bank_mask:0xf
	v_fmac_f32_dpp v234, v54, v198 row_shr:1 row_mask:0xf bank_mask:0xf
	v_fmac_f32_dpp v235, v55, v199 row_shr:1 row_mask:0xf bank_mask:0xf
	v_fmac_f32_dpp v232, v62, v158 row_shr:2 row_mask:0xf bank_mask:0xf
	v_fmac_f32_dpp v233, v63, v159 row_shr:2 row_mask:0xf bank_mask:0xf
	v_fmac_f32_dpp v234, v54, v190 row_shr:2 row_mask:0xf bank_mask:0xf
	v_fmac_f32_dpp v235, v55, v191 row_shr:2 row_mask:0xf bank_mask:0xf
	v_mul_f32_e32 v246, v236, v232
	v_mul_f32_e32 v247, v236, v233
	v_exp_f32_e32 v246, v246
	v_exp_f32_e32 v247, v247
	s_nop 0
	v_pk_add_f32 v[246:247], v[246:247], v[238:239]
	v_rcp_f32_e32 v246, v246
	v_rcp_f32_e32 v247, v247
; __device__ __forceinline__ unsigned cvt_pk_bf16(float lo, float hi) { unsigned r; asm("v_cvt_pk_bf16_f32 %0, %1, %2" : "=v"(r) : "v"(lo), "v"(hi)); return r; }
; __device__ __forceinline__ float sigmoid_f(float v) { return __builtin_amdgcn_rcpf(1.0f + __builtin_amdgcn_exp2f(-1.4426950409f * v)); }
; __device__ __forceinline__ f32x4 bf4(u32x2 w) { return (f32x4){bf_lo(w.x), bf_hi(w.x), bf_lo(w.y), bf_hi(w.y)}; }
; __device__ __forceinline__ void phase10(const Args& a, int G, int wv, bool dummy = false) {
;     ...
;             for (int t = 0; t < 8; ++t) { const f32x4 gc = bf4(gr[t]), vc = bf4(vr[t]);
;                 const f32x4 gg = wg0 * gm2 + wg1 * gm1 + wg2 * gc + bg, vv = wv0 * vm2 + wv1 * vm1 + wv2 * vc + bv;
;                 f32x4 o;
; #pragma unroll
;                 for (int e = 0; e < 4; ++e) o[e] = gg[e] * pg8::sigmoid_f(gg[e]) * vv[e];
;                 u32x2 w; w.x = cvt_pk_bf16(o[0], o[1]); w.y = cvt_pk_bf16(o[2], o[3]);
;                 if (dummy) *(u32x2*)((bf16_t*)(a.ws + WS_D) + ((((size_t)(row0 + t0 + t)) * 5632 + ch) & (size_t)0x1ffffff)) = w; else *(u32x2*)(up + (size_t)(t0 + t) * 5632) = w;
	v_pk_mul_f32 v[232:233], v[232:233], v[234:235]
	v_pk_mul_f32 v[232:233], v[232:233], v[246:247]
	v_cvt_pk_bf16_f32 v61, v232, v233
	v_pk_fma_f32 v[232:233], v[8:9], v[176:177], v[184:185]
	v_pk_fma_f32 v[234:235], v[0:1], v[208:209], v[216:217]
	s_nop 1
	v_fmac_f32_dpp v232, v8, v168 row_shr:1 row_mask:0xf bank_mask:0xf
	v_fmac_f32_dpp v233, v9, v169 row_shr:1 row_mask:0xf bank_mask:0xf
	v_fmac_f32_dpp v234, v0, v200 row_shr:1 row_mask:0xf bank_mask:0xf
	v_fmac_f32_dpp v235, v1, v201 row_shr:1 row_mask:0xf bank_mask:0xf
	v_fmac_f32_dpp v232, v8, v160 row_shr:2 row_mask:0xf bank_mask:0xf
	v_fmac_f32_dpp v233, v9, v161 row_shr:2 row_mask:0xf bank_mask:0xf
	v_fmac_f32_dpp v234, v0, v192 row_shr:2 row_mask:0xf bank_mask:0xf
	v_fmac_f32_dpp v235, v1, v193 row_shr:2 row_mask:0xf bank_mask:0xf
	v_fmac_f32_dpp v232, v24, v168 row_shl:15 row_mask:0xf bank_mask:0xf
	v_fmac_f32_dpp v233, v25, v169 row_shl:15 row_mask:0xf bank_mask:0xf
	v_fmac_f32_dpp v234, v12, v200 row_shl:15 row_mask:0xf bank_mask:0xf
	v_fmac_f32_dpp v235, v13, v201 row_shl:15 row_mask:0xf bank_mask:0xf
	v_fmac_f32_dpp v232, v24, v160 row_shl:14 row_mask:0xf bank_mask:0xf
	v_fmac_f32_dpp v233, v25, v161 row_shl:14 row_mask:0xf bank_mask:0xf
	v_fmac_f32_dpp v234, v12, v192 row_shl:14 row_mask:0xf bank_mask:0xf
	v_fmac_f32_dpp v235, v13, v193 row_shl:14 row_mask:0xf bank_mask:0xf
	v_mul_f32_e32 v246, v236, v232
	v_mul_f32_e32 v247, v236, v233
	v_exp_f32_e32 v246, v246
	v_exp_f32_e32 v247, v247
	s_nop 0
	v_pk_add_f32 v[246:247], v[246:247], v[238:239]
	v_rcp_f32_e32 v246, v246
	v_rcp_f32_e32 v247, v247
	v_pk_mul_f32 v[232:233], v[232:233], v[234:235]
	v_pk_mul_f32 v[232:233], v[232:233], v[246:247]
	v_cvt_pk_bf16_f32 v18, v232, v233
	v_pk_fma_f32 v[232:233], v[24:25], v[176:177], v[184:185]
	v_pk_fma_f32 v[234:235], v[12:13], v[208:209], v[216:217]
	s_nop 1
	v_fmac_f32_dpp v232, v24, v168 row_shr:1 row_mask:0xf bank_mask:0xf
	v_fmac_f32_dpp v233, v25, v169 row_shr:1 row_mask:0xf bank_mask:0xf
	v_fmac_f32_dpp v234, v12, v200 row_shr:1 row_mask:0xf bank_mask:0xf
	v_fmac_f32_dpp v235, v13, v201 row_shr:1 row_mask:0xf bank_mask:0xf
	v_fmac_f32_dpp v232, v24, v160 row_shr:2 row_mask:0xf bank_mask:0xf
	v_fmac_f32_dpp v233, v25, v161 row_shr:2 row_mask:0xf bank_mask:0xf
	v_fmac_f32_dpp v234, v12, v192 row_shr:2 row_mask:0xf bank_mask:0xf
	v_fmac_f32_dpp v235, v13, v193 row_shr:2 row_mask:0xf bank_mask:0xf
	v_fmac_f32_dpp v232, v40, v168 row_shl:15 row_mask:0xf bank_mask:0xf
	v_fmac_f32_dpp v233, v41, v169 row_shl:15 row_mask:0xf bank_mask:0xf
	v_fmac_f32_dpp v234, v28, v200 row_shl:15 row_mask:0xf bank_mask:0xf
	v_fmac_f32_dpp v235, v29, v201 row_shl:15 row_mask:0xf bank_mask:0xf
	v_fmac_f32_dpp v232, v40, v160 row_shl:14 row_mask:0xf bank_mask:0xf
	v_fmac_f32_dpp v233, v41, v161 row_shl:14 row_mask:0xf bank_mask:0xf
	v_fmac_f32_dpp v234, v28, v192 row_shl:14 row_mask:0xf bank_mask:0xf
	v_fmac_f32_dpp v235, v29, v193 row_shl:14 row_mask:0xf bank_mask:0xf
	v_mul_f32_e32 v246, v236, v232
	v_mul_f32_e32 v247, v236, v233
	v_exp_f32_e32 v246, v246
	v_exp_f32_e32 v247, v247
	s_nop 0
	v_pk_add_f32 v[246:247], v[246:247], v[238:239]
	v_rcp_f32_e32 v246, v246
	v_rcp_f32_e32 v247, v247
	v_pk_mul_f32 v[232:233], v[232:233], v[234:235]
	v_pk_mul_f32 v[232:233], v[232:233], v[246:247]
	v_cvt_pk_bf16_f32 v34, v232, v233
	v_pk_fma_f32 v[232:233], v[40:41], v[176:177], v[184:185]
	v_pk_fma_f32 v[234:235], v[28:29], v[208:209], v[216:217]
	s_nop 1
	v_fmac_f32_dpp v232, v40, v168 row_shr:1 row_mask:0xf bank_mask:0xf
	v_fmac_f32_dpp v233, v41, v169 row_shr:1 row_mask:0xf bank_mask:0xf
	v_fmac_f32_dpp v234, v28, v200 row_shr:1 row_mask:0xf bank_mask:0xf
	v_fmac_f32_dpp v235, v29, v201 row_shr:1 row_mask:0xf bank_mask:0xf
	v_fmac_f32_dpp v232, v40, v160 row_shr:2 row_mask:0xf bank_mask:0xf
	v_fmac_f32_dpp v233, v41, v161 row_shr:2 row_mask:0xf bank_mask:0xf
	v_fmac_f32_dpp v234, v28, v192 row_shr:2 row_mask:0xf bank_mask:0xf
	v_fmac_f32_dpp v235, v29, v193 row_shr:2 row_mask:0xf bank_mask:0xf
	v_fmac_f32_dpp v232, v56, v168 row_shl:15 row_mask:0xf bank_mask:0xf
	v_fmac_f32_dpp v233, v57, v169 row_shl:15 row_mask:0xf bank_mask:0xf
	v_fmac_f32_dpp v234, v44, v200 row_shl:15 row_mask:0xf bank_mask:0xf
	v_fmac_f32_dpp v235, v45, v201 row_shl:15 row_mask:0xf bank_mask:0xf
	v_fmac_f32_dpp v232, v56, v160 row_shl:14 row_mask:0xf bank_mask:0xf
	v_fmac_f32_dpp v233, v57, v161 row_shl:14 row_mask:0xf bank_mask:0xf
	v_fmac_f32_dpp v234, v44, v192 row_shl:14 row_mask:0xf bank_mask:0xf
	v_fmac_f32_dpp v235, v45, v193 row_shl:14 row_mask:0xf bank_mask:0xf
	v_mul_f32_e32 v246, v236, v232
	v_mul_f32_e32 v247, v236, v233
	v_exp_f32_e32 v246, v246
	v_exp_f32_e32 v247, v247
	s_nop 0
	v_pk_add_f32 v[246:247], v[246:247], v[238:239]
	v_rcp_f32_e32 v246, v246
	v_rcp_f32_e32 v247, v247
	v_pk_mul_f32 v[232:233], v[232:233], v[234:235]
	v_pk_mul_f32 v[232:233], v[232:233], v[246:247]
	v_cvt_pk_bf16_f32 v50, v232, v233
	v_pk_fma_f32 v[232:233], v[56:57], v[176:177], v[184:185]
	v_pk_fma_f32 v[234:235], v[44:45], v[208:209], v[216:217]
	s_nop 1
	v_fmac_f32_dpp v232, v56, v168 row_shr:1 row_mask:0xf bank_mask:0xf
	v_fmac_f32_dpp v233, v57, v169 row_shr:1 row_mask:0xf bank_mask:0xf
	v_fmac_f32_dpp v234, v44, v200 row_shr:1 row_mask:0xf bank_mask:0xf
	v_fmac_f32_dpp v235, v45, v201 row_shr:1 row_mask:0xf bank_mask:0xf
	v_fmac_f32_dpp v232, v56, v160 row_shr:2 row_mask:0xf bank_mask:0xf
	v_fmac_f32_dpp v233, v57, v161 row_shr:2 row_mask:0xf bank_mask:0xf
	v_fmac_f32_dpp v234, v44, v192 row_shr:2 row_mask:0xf bank_mask:0xf
	v_fmac_f32_dpp v235, v45, v193 row_shr:2 row_mask:0xf bank_mask:0xf
	v_mul_f32_e32 v246, v236, v232
; __device__ __forceinline__ unsigned cvt_pk_bf16(float lo, float hi) { unsigned r; asm("v_cvt_pk_bf16_f32 %0, %1, %2" : "=v"(r) : "v"(lo), "v"(hi)); return r; }
; __device__ __forceinline__ float sigmoid_f(float v) { return __builtin_amdgcn_rcpf(1.0f + __builtin_amdgcn_exp2f(-1.4426950409f * v)); }
; __device__ __forceinline__ u32x4 pack8(f32x4 a, f32x4 b) { u32x4 w; w.x = cvt_pk_bf16(a[0], a[1]); w.y = cvt_pk_bf16(a[2], a[3]); w.z = cvt_pk_bf16(b[0], b[1]); w.w = cvt_pk_bf16(b[2], b[3]); return w; }
; __device__ __forceinline__ f32x4 bf4(u32x2 w) { return (f32x4){bf_lo(w.x), bf_hi(w.x), bf_lo(w.y), bf_hi(w.y)}; }
;     __device__ __forceinline__ void operator()(const f32x4 (&acc)[2][2][4][2], const Unit& u, int wr, int wc, int fr, int fq) const {
;     ...
;             for (int m = 0; m < 4; ++m) { const int row = row0 + ai * HALF + m * 16; bf16_t* rowp = UP + (size_t)row * 5632 + u.pn * HALF + wc * 32 + 8 * fq;
; #pragma unroll
;                 for (int bj = 0; bj < 2; ++bj) { const u32x4 w = pack8(acc[ai][bj][m][0], acc[ai][bj][m][1]); __builtin_nontemporal_store(w, (u32x4*)(rowp + (size_t)bj * ((size_t)16384 * 5632)));
; __device__ __forceinline__ void phase10(const Args& a, int G, int wv, bool dummy = false) {
;     ...
;             for (int t = 0; t < 8; ++t) { const f32x4 gc = bf4(gr[t]), vc = bf4(vr[t]);
;                 const f32x4 gg = wg0 * gm2 + wg1 * gm1 + wg2 * gc + bg, vv = wv0 * vm2 + wv1 * vm1 + wv2 * vc + bv;
;                 f32x4 o;
; #pragma unroll
;                 for (int e = 0; e < 4; ++e) o[e] = gg[e] * pg8::sigmoid_f(gg[e]) * vv[e];
;                 u32x2 w; w.x = cvt_pk_bf16(o[0], o[1]); w.y = cvt_pk_bf16(o[2], o[3]);
;                 if (dummy) *(u32x2*)((bf16_t*)(a.ws + WS_D) + ((((size_t)(row0 + t0 + t)) * 5632 + ch) & (size_t)0x1ffffff)) = w; else *(u32x2*)(up + (size_t)(t0 + t) * 5632) = w;
	v_mul_f32_e32 v247, v236, v233
	v_exp_f32_e32 v246, v246
	v_exp_f32_e32 v247, v247
	s_nop 0
	v_pk_add_f32 v[246:247], v[246:247], v[238:239]
	v_rcp_f32_e32 v246, v246
	v_rcp_f32_e32 v247, v247
	v_pk_mul_f32 v[232:233], v[232:233], v[234:235]
	v_pk_mul_f32 v[232:233], v[232:233], v[246:247]
	v_cvt_pk_bf16_f32 v62, v232, v233
	v_pk_fma_f32 v[232:233], v[10:11], v[178:179], v[186:187]
	v_pk_fma_f32 v[234:235], v[2:3], v[210:211], v[218:219]
	s_nop 1
	v_fmac_f32_dpp v232, v10, v170 row_shr:1 row_mask:0xf bank_mask:0xf
	v_fmac_f32_dpp v233, v11, v171 row_shr:1 row_mask:0xf bank_mask:0xf
	v_fmac_f32_dpp v234, v2, v202 row_shr:1 row_mask:0xf bank_mask:0xf
	v_fmac_f32_dpp v235, v3, v203 row_shr:1 row_mask:0xf bank_mask:0xf
	v_fmac_f32_dpp v232, v10, v162 row_shr:2 row_mask:0xf bank_mask:0xf
	v_fmac_f32_dpp v233, v11, v163 row_shr:2 row_mask:0xf bank_mask:0xf
	v_fmac_f32_dpp v234, v2, v194 row_shr:2 row_mask:0xf bank_mask:0xf
	v_fmac_f32_dpp v235, v3, v195 row_shr:2 row_mask:0xf bank_mask:0xf
	v_fmac_f32_dpp v232, v26, v170 row_shl:15 row_mask:0xf bank_mask:0xf
	v_fmac_f32_dpp v233, v27, v171 row_shl:15 row_mask:0xf bank_mask:0xf
	v_fmac_f32_dpp v234, v14, v202 row_shl:15 row_mask:0xf bank_mask:0xf
	v_fmac_f32_dpp v235, v15, v203 row_shl:15 row_mask:0xf bank_mask:0xf
	v_fmac_f32_dpp v232, v26, v162 row_shl:14 row_mask:0xf bank_mask:0xf
	v_fmac_f32_dpp v233, v27, v163 row_shl:14 row_mask:0xf bank_mask:0xf
	v_fmac_f32_dpp v234, v14, v194 row_shl:14 row_mask:0xf bank_mask:0xf
	v_fmac_f32_dpp v235, v15, v195 row_shl:14 row_mask:0xf bank_mask:0xf
	v_mul_f32_e32 v246, v236, v232
	v_mul_f32_e32 v247, v236, v233
	v_exp_f32_e32 v246, v246
	v_exp_f32_e32 v247, v247
	s_nop 0
	v_pk_add_f32 v[246:247], v[246:247], v[238:239]
	v_rcp_f32_e32 v246, v246
	v_rcp_f32_e32 v247, v247
	v_pk_mul_f32 v[232:233], v[232:233], v[234:235]
	v_pk_mul_f32 v[232:233], v[232:233], v[246:247]
	v_cvt_pk_bf16_f32 v19, v232, v233
	v_pk_fma_f32 v[232:233], v[26:27], v[178:179], v[186:187]
	v_pk_fma_f32 v[234:235], v[14:15], v[210:211], v[218:219]
	s_nop 1
	v_fmac_f32_dpp v232, v26, v170 row_shr:1 row_mask:0xf bank_mask:0xf
	v_fmac_f32_dpp v233, v27, v171 row_shr:1 row_mask:0xf bank_mask:0xf
	v_fmac_f32_dpp v234, v14, v202 row_shr:1 row_mask:0xf bank_mask:0xf
	v_fmac_f32_dpp v235, v15, v203 row_shr:1 row_mask:0xf bank_mask:0xf
	v_fmac_f32_dpp v232, v26, v162 row_shr:2 row_mask:0xf bank_mask:0xf
	v_fmac_f32_dpp v233, v27, v163 row_shr:2 row_mask:0xf bank_mask:0xf
	v_fmac_f32_dpp v234, v14, v194 row_shr:2 row_mask:0xf bank_mask:0xf
	v_fmac_f32_dpp v235, v15, v195 row_shr:2 row_mask:0xf bank_mask:0xf
	v_fmac_f32_dpp v232, v42, v170 row_shl:15 row_mask:0xf bank_mask:0xf
	v_fmac_f32_dpp v233, v43, v171 row_shl:15 row_mask:0xf bank_mask:0xf
	v_fmac_f32_dpp v234, v30, v202 row_shl:15 row_mask:0xf bank_mask:0xf
	v_fmac_f32_dpp v235, v31, v203 row_shl:15 row_mask:0xf bank_mask:0xf
	v_fmac_f32_dpp v232, v42, v162 row_shl:14 row_mask:0xf bank_mask:0xf
	v_fmac_f32_dpp v233, v43, v163 row_shl:14 row_mask:0xf bank_mask:0xf
	v_fmac_f32_dpp v234, v30, v194 row_shl:14 row_mask:0xf bank_mask:0xf
	v_fmac_f32_dpp v235, v31, v195 row_shl:14 row_mask:0xf bank_mask:0xf
	v_mul_f32_e32 v246, v236, v232
	v_mul_f32_e32 v247, v236, v233
	v_exp_f32_e32 v246, v246
	v_exp_f32_e32 v247, v247
	s_nop 0
	v_pk_add_f32 v[246:247], v[246:247], v[238:239]
	v_rcp_f32_e32 v246, v246
	v_rcp_f32_e32 v247, v247
	v_pk_mul_f32 v[232:233], v[232:233], v[234:235]
	v_pk_mul_f32 v[232:233], v[232:233], v[246:247]
	v_cvt_pk_bf16_f32 v35, v232, v233
	v_pk_fma_f32 v[232:233], v[42:43], v[178:179], v[186:187]
	v_pk_fma_f32 v[234:235], v[30:31], v[210:211], v[218:219]
	s_nop 1
	v_fmac_f32_dpp v232, v42, v170 row_shr:1 row_mask:0xf bank_mask:0xf
	v_fmac_f32_dpp v233, v43, v171 row_shr:1 row_mask:0xf bank_mask:0xf
	v_fmac_f32_dpp v234, v30, v202 row_shr:1 row_mask:0xf bank_mask:0xf
	v_fmac_f32_dpp v235, v31, v203 row_shr:1 row_mask:0xf bank_mask:0xf
	v_fmac_f32_dpp v232, v42, v162 row_shr:2 row_mask:0xf bank_mask:0xf
	v_fmac_f32_dpp v233, v43, v163 row_shr:2 row_mask:0xf bank_mask:0xf
	v_fmac_f32_dpp v234, v30, v194 row_shr:2 row_mask:0xf bank_mask:0xf
	v_fmac_f32_dpp v235, v31, v195 row_shr:2 row_mask:0xf bank_mask:0xf
	v_fmac_f32_dpp v232, v58, v170 row_shl:15 row_mask:0xf bank_mask:0xf
	v_fmac_f32_dpp v233, v59, v171 row_shl:15 row_mask:0xf bank_mask:0xf
	v_fmac_f32_dpp v234, v46, v202 row_shl:15 row_mask:0xf bank_mask:0xf
	v_fmac_f32_dpp v235, v47, v203 row_shl:15 row_mask:0xf bank_mask:0xf
	v_fmac_f32_dpp v232, v58, v162 row_shl:14 row_mask:0xf bank_mask:0xf
	v_fmac_f32_dpp v233, v59, v163 row_shl:14 row_mask:0xf bank_mask:0xf
	v_fmac_f32_dpp v234, v46, v194 row_shl:14 row_mask:0xf bank_mask:0xf
	v_fmac_f32_dpp v235, v47, v195 row_shl:14 row_mask:0xf bank_mask:0xf
	v_mul_f32_e32 v246, v236, v232
	v_mul_f32_e32 v247, v236, v233
	v_exp_f32_e32 v246, v246
	v_exp_f32_e32 v247, v247
	s_nop 0
	v_pk_add_f32 v[246:247], v[246:247], v[238:239]
	v_rcp_f32_e32 v246, v246
	v_rcp_f32_e32 v247, v247
	v_pk_mul_f32 v[232:233], v[232:233], v[234:235]
	v_pk_mul_f32 v[232:233], v[232:233], v[246:247]
	v_cvt_pk_bf16_f32 v51, v232, v233
	v_pk_fma_f32 v[232:233], v[58:59], v[178:179], v[186:187]
	v_pk_fma_f32 v[234:235], v[46:47], v[210:211], v[218:219]
	s_nop 1
	v_fmac_f32_dpp v232, v58, v170 row_shr:1 row_mask:0xf bank_mask:0xf
	v_fmac_f32_dpp v233, v59, v171 row_shr:1 row_mask:0xf bank_mask:0xf
	v_fmac_f32_dpp v234, v46, v202 row_shr:1 row_mask:0xf bank_mask:0xf
	v_fmac_f32_dpp v235, v47, v203 row_shr:1 row_mask:0xf bank_mask:0xf
	v_fmac_f32_dpp v232, v58, v162 row_shr:2 row_mask:0xf bank_mask:0xf
	v_fmac_f32_dpp v233, v59, v163 row_shr:2 row_mask:0xf bank_mask:0xf
	v_fmac_f32_dpp v234, v46, v194 row_shr:2 row_mask:0xf bank_mask:0xf
	v_fmac_f32_dpp v235, v47, v195 row_shr:2 row_mask:0xf bank_mask:0xf
	v_mul_f32_e32 v246, v236, v232
	v_mul_f32_e32 v247, v236, v233
	v_exp_f32_e32 v246, v246
	v_exp_f32_e32 v247, v247
	s_nop 0
	v_pk_add_f32 v[246:247], v[246:247], v[238:239]
	v_rcp_f32_e32 v246, v246
	v_rcp_f32_e32 v247, v247
	v_pk_mul_f32 v[232:233], v[232:233], v[234:235]
	v_pk_mul_f32 v[232:233], v[232:233], v[246:247]
	v_cvt_pk_bf16_f32 v63, v232, v233
	s_add_u32 s36, s100, 0x160000
	s_addc_u32 s37, s101, 0
	s_andn2_b64 exec, exec, s[64:65]
	global_store_dwordx4 v149, v[60:63], s[36:37]
	s_mov_b64 exec, -1
	s_add_u32 s36, s100, 0x18c000
	s_addc_u32 s37, s101, 0
	global_store_dwordx4 v149, v[48:51], s[36:37]
	s_add_u32 s36, s100, 0x1b8000
	s_addc_u32 s37, s101, 0
	global_store_dwordx4 v149, v[32:35], s[36:37]
	s_add_u32 s36, s100, 0x1e4000
	s_addc_u32 s37, s101, 0
	global_store_dwordx4 v149, v[16:19], s[36:37]
	s_andn2_b64 vcc, exec, s[4:5]
	s_mov_b64 s[4:5], -1
	s_cbranch_vccnz .LBB0_961
	s_andn2_b64 vcc, exec, s[10:11]
	s_cbranch_vccnz .LBB0_960
	s_barrier
	s_branch .LBB0_960
